# baseline (speedup 1.0000x reference)
; __device__ __forceinline__ unsigned pk2(float lo, float hi) { return f2bf(lo) | (f2bf(hi) << 16); }
; __device__ __forceinline__ float gelu_tanh(float x) {
;     const float u = 0.7978845608028654f * (x + 0.044715f * x * x * x);
;     const float e = __expf(2.0f * u);
;     const float th = 1.0f - 2.0f * __builtin_amdgcn_rcpf(e + 1.0f);
;     return 0.5f * x * (1.0f + th);
; }
; __device__ __forceinline__ void gmlp_fast(KArgs ap, int l, LAS unsigned char* lds, const Ctx cx) {
;     ...
; #pragma unroll
;             for (int ht = 0; ht < 4; ++ht)
; #pragma unroll
;                 for (int q4 = 0; q4 < 4; ++q4) { const u32x2 uu = *(const u32x2*)(zu + ht * 32 + 8 * q4);
;                     const float o0 = gelu_tanh(bflo(uu.x)) * (acc[ht][4 * q4] + bsv), o1 = gelu_tanh(bfhi(uu.x)) * (acc[ht][4 * q4 + 1] + bsv);
;                     const float o2 = gelu_tanh(bflo(uu.y)) * (acc[ht][4 * q4 + 2] + bsv), o3 = gelu_tanh(bfhi(uu.y)) * (acc[ht][4 * q4 + 3] + bsv);
;                     u32x2 w; w.x = pk2(o0, o1); w.y = pk2(o2, o3); *(u32x2*)(yo + ht * 32 + 8 * q4) = w; }
.LBB0_160:
	s_lshl_b32 s20, s20, 7
	s_ashr_i32 s21, s20, 31
	v_or_b32_e32 v64, s20, v80
	s_lshl_b64 s[20:21], s[20:21], 1
	v_lshl_add_u64 v[68:69], v[94:95], 0, s[20:21]
	global_load_dwordx2 v[70:71], v[68:69], off offset:3584
	v_ashrrev_i32_e32 v65, 31, v64
	v_lshl_add_u64 v[64:65], v[64:65], 2, s[14:15]
	global_load_dword v64, v[64:65], off
	global_load_dwordx2 v[200:201], v[68:69], off offset:3600
	global_load_dwordx2 v[202:203], v[68:69], off offset:3616
	global_load_dwordx2 v[204:205], v[68:69], off offset:3632
	global_load_dwordx2 v[206:207], v[68:69], off offset:3648
	global_load_dwordx2 v[208:209], v[68:69], off offset:3664
	global_load_dwordx2 v[210:211], v[68:69], off offset:3680
	global_load_dwordx2 v[212:213], v[68:69], off offset:3696
	global_load_dwordx2 v[214:215], v[68:69], off offset:3712
	global_load_dwordx2 v[216:217], v[68:69], off offset:3728
	global_load_dwordx2 v[218:219], v[68:69], off offset:3744
	global_load_dwordx2 v[220:221], v[68:69], off offset:3760
	global_load_dwordx2 v[222:223], v[68:69], off offset:3776
	global_load_dwordx2 v[224:225], v[68:69], off offset:3792
	global_load_dwordx2 v[226:227], v[68:69], off offset:3808
	global_load_dwordx2 v[228:229], v[68:69], off offset:3824
	v_lshl_add_u64 v[66:67], v[96:97], 0, s[20:21]
	s_mov_b32 s13, 1
	s_mov_b64 s[20:21], 0
	s_and_b64 vcc, exec, s[0:1]
	s_waitcnt vmcnt(16)
	v_lshlrev_b32_e32 v72, 16, v70
	v_mul_f32_e32 v65, 0x3d372713, v72
	v_mul_f32_e32 v65, v65, v72
	v_mov_b32_e32 v74, v72
	v_fmac_f32_e32 v74, v65, v74
	v_mul_f32_e32 v65, 0x3f4c422a, v74
	v_add_f32_e32 v65, v65, v65
	v_mul_f32_e32 v65, 0x3fb8aa3b, v65
	v_exp_f32_e32 v65, v65
	v_and_b32_e32 v70, 0xffff0000, v70
	v_mov_b32_e32 v75, v70
	v_lshlrev_b32_e32 v73, 16, v71
	v_add_f32_e32 v65, 1.0, v65
	v_rcp_f32_e32 v74, v65
	v_mul_f32_e32 v65, 0x3d372713, v70
	v_mul_f32_e32 v65, v65, v70
	v_fmac_f32_e32 v75, v65, v75
	v_mul_f32_e32 v65, 0x3f4c422a, v75
	v_add_f32_e32 v65, v65, v65
	v_mul_f32_e32 v65, 0x3fb8aa3b, v65
	v_exp_f32_e32 v65, v65
	v_mov_b32_e32 v75, v73
	v_and_b32_e32 v71, 0xffff0000, v71
	v_add_f32_e32 v65, 1.0, v65
	v_rcp_f32_e32 v76, v65
	v_mul_f32_e32 v65, 0x3d372713, v73
	v_mul_f32_e32 v65, v65, v73
	v_fmac_f32_e32 v75, v65, v75
	v_mul_f32_e32 v65, 0x3f4c422a, v75
	v_add_f32_e32 v65, v65, v65
	v_mul_f32_e32 v65, 0x3fb8aa3b, v65
	v_exp_f32_e32 v65, v65
	v_pk_mul_f32 v[72:73], v[72:73], 0.5 op_sel_hi:[1,0]
	v_add_f32_e32 v65, 1.0, v65
	v_rcp_f32_e32 v75, v65
	s_nop 0
	v_pk_fma_f32 v[74:75], v[74:75], 2.0, 1.0 op_sel_hi:[1,0,0] neg_lo:[1,0,0] neg_hi:[1,0,0]
	s_nop 0
	v_pk_add_f32 v[74:75], v[74:75], 1.0 op_sel_hi:[1,0]
	s_nop 0
	v_pk_mul_f32 v[72:73], v[72:73], v[74:75]
	v_mov_b32_e32 v74, v48
	v_mul_f32_e32 v48, 0x3d372713, v71
	v_mov_b32_e32 v75, v50
	v_mul_f32_e32 v48, v48, v71
	v_mov_b32_e32 v50, v71
	v_fmac_f32_e32 v50, v48, v50
	v_mul_f32_e32 v48, 0x3f4c422a, v50
	v_add_f32_e32 v48, v48, v48
	v_mul_f32_e32 v48, 0x3fb8aa3b, v48
	v_exp_f32_e32 v48, v48
	s_waitcnt vmcnt(15)
	v_pk_add_f32 v[74:75], v[74:75], v[64:65] op_sel_hi:[1,0]
	v_pk_mul_f32 v[70:71], v[70:71], 0.5 op_sel_hi:[1,0]
	v_pk_mul_f32 v[72:73], v[74:75], v[72:73]
	v_add_f32_e32 v48, 1.0, v48
	v_rcp_f32_e32 v77, v48
	v_mov_b32_e32 v50, v49
	v_pk_add_f32 v[48:49], v[50:51], v[64:65] op_sel_hi:[1,0]
	v_pk_fma_f32 v[74:75], v[76:77], 2.0, 1.0 op_sel_hi:[1,0,0] neg_lo:[1,0,0] neg_hi:[1,0,0]
	s_nop 0
	v_pk_add_f32 v[74:75], v[74:75], 1.0 op_sel_hi:[1,0]
	s_nop 0
	v_pk_mul_f32 v[70:71], v[70:71], v[74:75]
	s_nop 0
	v_pk_mul_f32 v[48:49], v[48:49], v[70:71]
	s_nop 0
	v_cvt_pk_bf16_f32 v49, v73, v49
	v_cvt_pk_bf16_f32 v48, v72, v48
	global_store_dwordx2 v[66:67], v[48:49], off
	s_waitcnt vmcnt(15)
	v_mov_b32_e32 v48, v200
	v_mov_b32_e32 v49, v201
	v_lshlrev_b32_e32 v50, 16, v48
	v_mul_f32_e32 v65, 0x3d372713, v50
	v_mul_f32_e32 v65, v65, v50
	v_mov_b32_e32 v70, v50
	v_fmac_f32_e32 v70, v65, v70
	v_mul_f32_e32 v65, 0x3f4c422a, v70
	v_add_f32_e32 v65, v65, v65
	v_mul_f32_e32 v65, 0x3fb8aa3b, v65
	v_exp_f32_e32 v65, v65
	v_and_b32_e32 v48, 0xffff0000, v48
	v_mov_b32_e32 v71, v48
	v_lshlrev_b32_e32 v51, 16, v49
	v_add_f32_e32 v65, 1.0, v65
	v_rcp_f32_e32 v70, v65
	v_mul_f32_e32 v65, 0x3d372713, v48
	v_mul_f32_e32 v65, v65, v48
	v_fmac_f32_e32 v71, v65, v71
	v_mul_f32_e32 v65, 0x3f4c422a, v71
	v_add_f32_e32 v65, v65, v65
	v_mul_f32_e32 v65, 0x3fb8aa3b, v65
	v_exp_f32_e32 v65, v65
	v_mov_b32_e32 v71, v51
	v_and_b32_e32 v49, 0xffff0000, v49
	v_add_f32_e32 v65, 1.0, v65
	v_rcp_f32_e32 v72, v65
	v_mul_f32_e32 v65, 0x3d372713, v51
	v_mul_f32_e32 v65, v65, v51
	v_fmac_f32_e32 v71, v65, v71
	v_mul_f32_e32 v65, 0x3f4c422a, v71
	v_add_f32_e32 v65, v65, v65
	v_mul_f32_e32 v65, 0x3fb8aa3b, v65
	v_exp_f32_e32 v65, v65
	v_pk_mul_f32 v[50:51], v[50:51], 0.5 op_sel_hi:[1,0]
	v_add_f32_e32 v65, 1.0, v65
	v_rcp_f32_e32 v71, v65
	s_nop 0
	v_pk_fma_f32 v[70:71], v[70:71], 2.0, 1.0 op_sel_hi:[1,0,0] neg_lo:[1,0,0] neg_hi:[1,0,0]
	s_nop 0
	v_pk_add_f32 v[70:71], v[70:71], 1.0 op_sel_hi:[1,0]
	s_nop 0
	v_pk_mul_f32 v[50:51], v[50:51], v[70:71]
	v_mov_b32_e32 v70, v52
	v_mul_f32_e32 v52, 0x3d372713, v49
	v_mov_b32_e32 v71, v54
	v_mul_f32_e32 v52, v52, v49
	v_mov_b32_e32 v54, v49
	v_fmac_f32_e32 v54, v52, v54
	v_mul_f32_e32 v52, 0x3f4c422a, v54
	v_add_f32_e32 v52, v52, v52
	v_mul_f32_e32 v52, 0x3fb8aa3b, v52
	v_exp_f32_e32 v52, v52
	v_pk_add_f32 v[70:71], v[70:71], v[64:65] op_sel_hi:[1,0]
	v_pk_mul_f32 v[48:49], v[48:49], 0.5 op_sel_hi:[1,0]
	v_pk_mul_f32 v[50:51], v[70:71], v[50:51]
	v_add_f32_e32 v52, 1.0, v52
	v_rcp_f32_e32 v73, v52
	v_mov_b32_e32 v54, v53
	v_pk_add_f32 v[52:53], v[54:55], v[64:65] op_sel_hi:[1,0]
	v_pk_fma_f32 v[70:71], v[72:73], 2.0, 1.0 op_sel_hi:[1,0,0] neg_lo:[1,0,0] neg_hi:[1,0,0]
	s_nop 0
	v_pk_add_f32 v[70:71], v[70:71], 1.0 op_sel_hi:[1,0]
	s_nop 0
	v_pk_mul_f32 v[48:49], v[48:49], v[70:71]
	s_nop 0
	v_pk_mul_f32 v[48:49], v[52:53], v[48:49]
	v_and_b32_sdwa v52, v51, v196 dst_sel:DWORD dst_unused:UNUSED_PAD src0_sel:WORD_1 src1_sel:DWORD
	v_and_b32_sdwa v53, v50, v196 dst_sel:DWORD dst_unused:UNUSED_PAD src0_sel:WORD_1 src1_sel:DWORD
	s_nop 0
	v_add3_u32 v50, v50, v53, s45
	v_add3_u32 v51, v51, v52, s45
	v_and_b32_sdwa v52, v49, v196 dst_sel:DWORD dst_unused:UNUSED_PAD src0_sel:WORD_1 src1_sel:DWORD
	v_and_b32_sdwa v53, v48, v196 dst_sel:DWORD dst_unused:UNUSED_PAD src0_sel:WORD_1 src1_sel:DWORD
	v_add3_u32 v49, v49, v52, s45
	v_add3_u32 v48, v48, v53, s45
	v_and_b32_e32 v49, 0xffff0000, v49
	v_and_b32_e32 v48, 0xffff0000, v48
	v_or_b32_sdwa v49, v49, v51 dst_sel:DWORD dst_unused:UNUSED_PAD src0_sel:DWORD src1_sel:WORD_1
	v_or_b32_sdwa v48, v48, v50 dst_sel:DWORD dst_unused:UNUSED_PAD src0_sel:DWORD src1_sel:WORD_1
	global_store_dwordx2 v[66:67], v[48:49], off offset:16
	s_waitcnt vmcnt(15)
; __device__ __forceinline__ unsigned pk2(float lo, float hi) { return f2bf(lo) | (f2bf(hi) << 16); }
; __device__ __forceinline__ float gelu_tanh(float x) {
;     const float u = 0.7978845608028654f * (x + 0.044715f * x * x * x);
;     const float e = __expf(2.0f * u);
;     const float th = 1.0f - 2.0f * __builtin_amdgcn_rcpf(e + 1.0f);
;     return 0.5f * x * (1.0f + th);
; }
; __device__ __forceinline__ void gmlp_fast(KArgs ap, int l, LAS unsigned char* lds, const Ctx cx) {
;     ...
; #pragma unroll
;             for (int ht = 0; ht < 4; ++ht)
; #pragma unroll
;                 for (int q4 = 0; q4 < 4; ++q4) { const u32x2 uu = *(const u32x2*)(zu + ht * 32 + 8 * q4);
;                     const float o0 = gelu_tanh(bflo(uu.x)) * (acc[ht][4 * q4] + bsv), o1 = gelu_tanh(bfhi(uu.x)) * (acc[ht][4 * q4 + 1] + bsv);
;                     const float o2 = gelu_tanh(bflo(uu.y)) * (acc[ht][4 * q4 + 2] + bsv), o3 = gelu_tanh(bfhi(uu.y)) * (acc[ht][4 * q4 + 3] + bsv);
;                     u32x2 w; w.x = pk2(o0, o1); w.y = pk2(o2, o3); *(u32x2*)(yo + ht * 32 + 8 * q4) = w; }
	v_mov_b32_e32 v48, v202
	v_mov_b32_e32 v49, v203
	v_lshlrev_b32_e32 v50, 16, v48
	v_mul_f32_e32 v52, 0x3d372713, v50
	v_mul_f32_e32 v52, v52, v50
	v_mov_b32_e32 v53, v50
	v_fmac_f32_e32 v53, v52, v53
	v_and_b32_e32 v48, 0xffff0000, v48
	v_mul_f32_e32 v52, 0x3f4c422a, v53
	v_mul_f32_e32 v53, 0x3d372713, v48
	v_mul_f32_e32 v53, v53, v48
	v_mov_b32_e32 v54, v48
	v_fmac_f32_e32 v54, v53, v54
	v_mul_f32_e32 v53, 0x3f4c422a, v54
	v_add_f32_e32 v53, v53, v53
	v_mul_f32_e32 v53, 0x3fb8aa3b, v53
	v_exp_f32_e32 v53, v53
	v_lshlrev_b32_e32 v51, 16, v49
	v_mov_b32_e32 v55, v51
	v_add_f32_e32 v52, v52, v52
	v_add_f32_e32 v53, 1.0, v53
	v_rcp_f32_e32 v54, v53
	v_mul_f32_e32 v53, 0x3d372713, v51
	v_mul_f32_e32 v53, v53, v51
	v_fmac_f32_e32 v55, v53, v55
	v_mul_f32_e32 v53, 0x3f4c422a, v55
	v_add_f32_e32 v53, v53, v53
	v_mul_f32_e32 v52, 0x3fb8aa3b, v52
	v_mul_f32_e32 v53, 0x3fb8aa3b, v53
	v_exp_f32_e32 v52, v52
	v_exp_f32_e32 v53, v53
	v_pk_mul_f32 v[50:51], v[50:51], 0.5 op_sel_hi:[1,0]
	v_and_b32_e32 v49, 0xffff0000, v49
	v_add_f32_e32 v52, 1.0, v52
	v_add_f32_e32 v53, 1.0, v53
	v_rcp_f32_e32 v52, v52
	v_rcp_f32_e32 v53, v53
	s_nop 0
	v_pk_fma_f32 v[52:53], v[52:53], 2.0, 1.0 op_sel_hi:[1,0,0] neg_lo:[1,0,0] neg_hi:[1,0,0]
	s_nop 0
	v_pk_add_f32 v[52:53], v[52:53], 1.0 op_sel_hi:[1,0]
	s_nop 0
	v_pk_mul_f32 v[50:51], v[50:51], v[52:53]
	v_mov_b32_e32 v52, v56
	v_mov_b32_e32 v53, v58
	v_pk_add_f32 v[52:53], v[52:53], v[64:65] op_sel_hi:[1,0]
	v_mov_b32_e32 v58, v57
	v_pk_mul_f32 v[50:51], v[52:53], v[50:51]
	v_mul_f32_e32 v52, 0x3d372713, v49
	v_mul_f32_e32 v52, v52, v49
	v_mov_b32_e32 v53, v49
	v_fmac_f32_e32 v53, v52, v53
	v_mul_f32_e32 v52, 0x3f4c422a, v53
	v_add_f32_e32 v52, v52, v52
	v_mul_f32_e32 v52, 0x3fb8aa3b, v52
	v_exp_f32_e32 v52, v52
	v_pk_mul_f32 v[48:49], v[48:49], 0.5 op_sel_hi:[1,0]
	v_add_f32_e32 v52, 1.0, v52
	v_rcp_f32_e32 v55, v52
	s_nop 0
	v_pk_fma_f32 v[52:53], v[54:55], 2.0, 1.0 op_sel_hi:[1,0,0] neg_lo:[1,0,0] neg_hi:[1,0,0]
	s_nop 0
	v_pk_add_f32 v[52:53], v[52:53], 1.0 op_sel_hi:[1,0]
	s_nop 0
	v_pk_mul_f32 v[48:49], v[48:49], v[52:53]
	v_pk_add_f32 v[52:53], v[58:59], v[64:65] op_sel_hi:[1,0]
	s_nop 0
	v_pk_mul_f32 v[48:49], v[52:53], v[48:49]
	v_and_b32_sdwa v52, v51, v196 dst_sel:DWORD dst_unused:UNUSED_PAD src0_sel:WORD_1 src1_sel:DWORD
	v_and_b32_sdwa v53, v50, v196 dst_sel:DWORD dst_unused:UNUSED_PAD src0_sel:WORD_1 src1_sel:DWORD
	s_nop 0
	v_add3_u32 v50, v50, v53, s45
	v_add3_u32 v51, v51, v52, s45
	v_and_b32_sdwa v52, v49, v196 dst_sel:DWORD dst_unused:UNUSED_PAD src0_sel:WORD_1 src1_sel:DWORD
	v_and_b32_sdwa v53, v48, v196 dst_sel:DWORD dst_unused:UNUSED_PAD src0_sel:WORD_1 src1_sel:DWORD
	v_add3_u32 v49, v49, v52, s45
	v_add3_u32 v48, v48, v53, s45
	v_and_b32_e32 v49, 0xffff0000, v49
	v_and_b32_e32 v48, 0xffff0000, v48
	v_or_b32_sdwa v49, v49, v51 dst_sel:DWORD dst_unused:UNUSED_PAD src0_sel:DWORD src1_sel:WORD_1
	v_or_b32_sdwa v48, v48, v50 dst_sel:DWORD dst_unused:UNUSED_PAD src0_sel:DWORD src1_sel:WORD_1
	global_store_dwordx2 v[66:67], v[48:49], off offset:32
	s_waitcnt vmcnt(15)
	v_mov_b32_e32 v48, v204
	v_mov_b32_e32 v49, v205
	v_lshlrev_b32_e32 v50, 16, v48
	v_mul_f32_e32 v52, 0x3d372713, v50
	v_mul_f32_e32 v52, v52, v50
	v_mov_b32_e32 v53, v50
	v_fmac_f32_e32 v53, v52, v53
	v_and_b32_e32 v48, 0xffff0000, v48
	v_mul_f32_e32 v52, 0x3f4c422a, v53
	v_mul_f32_e32 v53, 0x3d372713, v48
	v_mul_f32_e32 v53, v53, v48
	v_mov_b32_e32 v54, v48
	v_fmac_f32_e32 v54, v53, v54
	v_mul_f32_e32 v53, 0x3f4c422a, v54
	v_add_f32_e32 v53, v53, v53
	v_mul_f32_e32 v53, 0x3fb8aa3b, v53
	v_exp_f32_e32 v53, v53
	v_lshlrev_b32_e32 v51, 16, v49
	v_mov_b32_e32 v55, v51
	v_add_f32_e32 v52, v52, v52
	v_add_f32_e32 v53, 1.0, v53
	v_rcp_f32_e32 v54, v53
	v_mul_f32_e32 v53, 0x3d372713, v51
	v_mul_f32_e32 v53, v53, v51
	v_fmac_f32_e32 v55, v53, v55
	v_mul_f32_e32 v53, 0x3f4c422a, v55
	v_add_f32_e32 v53, v53, v53
	v_mul_f32_e32 v52, 0x3fb8aa3b, v52
	v_mul_f32_e32 v53, 0x3fb8aa3b, v53
	v_exp_f32_e32 v52, v52
	v_exp_f32_e32 v53, v53
	v_pk_mul_f32 v[50:51], v[50:51], 0.5 op_sel_hi:[1,0]
	v_and_b32_e32 v49, 0xffff0000, v49
	v_add_f32_e32 v52, 1.0, v52
	v_add_f32_e32 v53, 1.0, v53
	v_rcp_f32_e32 v52, v52
	v_rcp_f32_e32 v53, v53
	s_nop 0
	v_pk_fma_f32 v[52:53], v[52:53], 2.0, 1.0 op_sel_hi:[1,0,0] neg_lo:[1,0,0] neg_hi:[1,0,0]
	s_nop 0
	v_pk_add_f32 v[52:53], v[52:53], 1.0 op_sel_hi:[1,0]
	s_nop 0
	v_pk_mul_f32 v[50:51], v[50:51], v[52:53]
	v_mov_b32_e32 v52, v60
	v_mov_b32_e32 v53, v62
	v_pk_add_f32 v[52:53], v[52:53], v[64:65] op_sel_hi:[1,0]
	v_mov_b32_e32 v62, v61
	v_pk_mul_f32 v[50:51], v[52:53], v[50:51]
	v_mul_f32_e32 v52, 0x3d372713, v49
	v_mul_f32_e32 v52, v52, v49
	v_mov_b32_e32 v53, v49
	v_fmac_f32_e32 v53, v52, v53
	v_mul_f32_e32 v52, 0x3f4c422a, v53
	v_add_f32_e32 v52, v52, v52
	v_mul_f32_e32 v52, 0x3fb8aa3b, v52
	v_exp_f32_e32 v52, v52
	v_pk_mul_f32 v[48:49], v[48:49], 0.5 op_sel_hi:[1,0]
	v_add_f32_e32 v52, 1.0, v52
	v_rcp_f32_e32 v55, v52
	s_nop 0
	v_pk_fma_f32 v[52:53], v[54:55], 2.0, 1.0 op_sel_hi:[1,0,0] neg_lo:[1,0,0] neg_hi:[1,0,0]
	s_nop 0
	v_pk_add_f32 v[52:53], v[52:53], 1.0 op_sel_hi:[1,0]
	s_nop 0
	v_pk_mul_f32 v[48:49], v[48:49], v[52:53]
	v_pk_add_f32 v[52:53], v[62:63], v[64:65] op_sel_hi:[1,0]
	s_nop 0
	v_pk_mul_f32 v[48:49], v[52:53], v[48:49]
	v_and_b32_sdwa v52, v51, v196 dst_sel:DWORD dst_unused:UNUSED_PAD src0_sel:WORD_1 src1_sel:DWORD
	v_and_b32_sdwa v53, v50, v196 dst_sel:DWORD dst_unused:UNUSED_PAD src0_sel:WORD_1 src1_sel:DWORD
	s_nop 0
	v_add3_u32 v50, v50, v53, s45
	v_add3_u32 v51, v51, v52, s45
	v_and_b32_sdwa v52, v49, v196 dst_sel:DWORD dst_unused:UNUSED_PAD src0_sel:WORD_1 src1_sel:DWORD
	v_and_b32_sdwa v53, v48, v196 dst_sel:DWORD dst_unused:UNUSED_PAD src0_sel:WORD_1 src1_sel:DWORD
	v_add3_u32 v49, v49, v52, s45
	v_add3_u32 v48, v48, v53, s45
	v_and_b32_e32 v49, 0xffff0000, v49
	v_and_b32_e32 v48, 0xffff0000, v48
	v_or_b32_sdwa v49, v49, v51 dst_sel:DWORD dst_unused:UNUSED_PAD src0_sel:DWORD src1_sel:WORD_1
	v_or_b32_sdwa v48, v48, v50 dst_sel:DWORD dst_unused:UNUSED_PAD src0_sel:DWORD src1_sel:WORD_1
	global_store_dwordx2 v[66:67], v[48:49], off offset:48
	s_waitcnt vmcnt(15)
; __device__ __forceinline__ unsigned pk2(float lo, float hi) { return f2bf(lo) | (f2bf(hi) << 16); }
; __device__ __forceinline__ float gelu_tanh(float x) {
;     const float u = 0.7978845608028654f * (x + 0.044715f * x * x * x);
;     const float e = __expf(2.0f * u);
;     const float th = 1.0f - 2.0f * __builtin_amdgcn_rcpf(e + 1.0f);
;     return 0.5f * x * (1.0f + th);
; }
; __device__ __forceinline__ void gmlp_fast(KArgs ap, int l, LAS unsigned char* lds, const Ctx cx) {
;     ...
; #pragma unroll
;             for (int ht = 0; ht < 4; ++ht)
; #pragma unroll
;                 for (int q4 = 0; q4 < 4; ++q4) { const u32x2 uu = *(const u32x2*)(zu + ht * 32 + 8 * q4);
;                     const float o0 = gelu_tanh(bflo(uu.x)) * (acc[ht][4 * q4] + bsv), o1 = gelu_tanh(bfhi(uu.x)) * (acc[ht][4 * q4 + 1] + bsv);
;                     const float o2 = gelu_tanh(bflo(uu.y)) * (acc[ht][4 * q4 + 2] + bsv), o3 = gelu_tanh(bfhi(uu.y)) * (acc[ht][4 * q4 + 3] + bsv);
;                     u32x2 w; w.x = pk2(o0, o1); w.y = pk2(o2, o3); *(u32x2*)(yo + ht * 32 + 8 * q4) = w; }
	v_mov_b32_e32 v48, v206
	v_mov_b32_e32 v49, v207
	v_lshlrev_b32_e32 v50, 16, v48
	v_mul_f32_e32 v52, 0x3d372713, v50
	v_mul_f32_e32 v52, v52, v50
	v_mov_b32_e32 v53, v50
	v_fmac_f32_e32 v53, v52, v53
	v_and_b32_e32 v48, 0xffff0000, v48
	v_mul_f32_e32 v52, 0x3f4c422a, v53
	v_mul_f32_e32 v53, 0x3d372713, v48
	v_mul_f32_e32 v53, v53, v48
	v_mov_b32_e32 v54, v48
	v_fmac_f32_e32 v54, v53, v54
	v_mul_f32_e32 v53, 0x3f4c422a, v54
	v_add_f32_e32 v53, v53, v53
	v_mul_f32_e32 v53, 0x3fb8aa3b, v53
	v_exp_f32_e32 v53, v53
	v_lshlrev_b32_e32 v51, 16, v49
	v_mov_b32_e32 v55, v51
	v_add_f32_e32 v52, v52, v52
	v_add_f32_e32 v53, 1.0, v53
	v_rcp_f32_e32 v54, v53
	v_mul_f32_e32 v53, 0x3d372713, v51
	v_mul_f32_e32 v53, v53, v51
	v_fmac_f32_e32 v55, v53, v55
	v_mul_f32_e32 v53, 0x3f4c422a, v55
	v_add_f32_e32 v53, v53, v53
	v_mul_f32_e32 v52, 0x3fb8aa3b, v52
	v_mul_f32_e32 v53, 0x3fb8aa3b, v53
	v_exp_f32_e32 v52, v52
	v_exp_f32_e32 v53, v53
	v_and_b32_e32 v49, 0xffff0000, v49
	v_pk_mul_f32 v[50:51], v[50:51], 0.5 op_sel_hi:[1,0]
	v_add_f32_e32 v52, 1.0, v52
	v_add_f32_e32 v53, 1.0, v53
	v_rcp_f32_e32 v52, v52
	v_rcp_f32_e32 v53, v53
	s_nop 0
	v_pk_fma_f32 v[52:53], v[52:53], 2.0, 1.0 op_sel_hi:[1,0,0] neg_lo:[1,0,0] neg_hi:[1,0,0]
	s_nop 0
	v_pk_add_f32 v[52:53], v[52:53], 1.0 op_sel_hi:[1,0]
	s_nop 0
	v_pk_mul_f32 v[50:51], v[50:51], v[52:53]
	v_mov_b32_e32 v52, v32
	v_mul_f32_e32 v32, 0x3d372713, v49
	v_mov_b32_e32 v53, v34
	v_mul_f32_e32 v32, v32, v49
	v_mov_b32_e32 v34, v49
	v_fmac_f32_e32 v34, v32, v34
	v_mul_f32_e32 v32, 0x3f4c422a, v34
	v_add_f32_e32 v32, v32, v32
	v_mul_f32_e32 v32, 0x3fb8aa3b, v32
	v_exp_f32_e32 v32, v32
	v_pk_add_f32 v[52:53], v[52:53], v[64:65] op_sel_hi:[1,0]
	v_pk_mul_f32 v[48:49], v[48:49], 0.5 op_sel_hi:[1,0]
	v_pk_mul_f32 v[50:51], v[52:53], v[50:51]
	v_add_f32_e32 v32, 1.0, v32
	v_rcp_f32_e32 v55, v32
	v_mov_b32_e32 v34, v33
	v_pk_add_f32 v[32:33], v[34:35], v[64:65] op_sel_hi:[1,0]
	v_pk_fma_f32 v[52:53], v[54:55], 2.0, 1.0 op_sel_hi:[1,0,0] neg_lo:[1,0,0] neg_hi:[1,0,0]
	s_nop 0
	v_pk_add_f32 v[52:53], v[52:53], 1.0 op_sel_hi:[1,0]
	s_nop 0
	v_pk_mul_f32 v[48:49], v[48:49], v[52:53]
	s_nop 0
	v_pk_mul_f32 v[32:33], v[32:33], v[48:49]
	s_nop 0
	v_cvt_pk_bf16_f32 v33, v51, v33
	v_cvt_pk_bf16_f32 v32, v50, v32
	global_store_dwordx2 v[66:67], v[32:33], off offset:64
	s_waitcnt vmcnt(15)
	v_mov_b32_e32 v32, v208
	v_mov_b32_e32 v33, v209
	v_lshlrev_b32_e32 v34, 16, v32
	v_mul_f32_e32 v48, 0x3d372713, v34
	v_mul_f32_e32 v48, v48, v34
	v_mov_b32_e32 v49, v34
	v_fmac_f32_e32 v49, v48, v49
	v_and_b32_e32 v32, 0xffff0000, v32
	v_mul_f32_e32 v48, 0x3f4c422a, v49
	v_mul_f32_e32 v49, 0x3d372713, v32
	v_mul_f32_e32 v49, v49, v32
	v_mov_b32_e32 v50, v32
	v_fmac_f32_e32 v50, v49, v50
	v_mul_f32_e32 v49, 0x3f4c422a, v50
	v_add_f32_e32 v49, v49, v49
	v_mul_f32_e32 v49, 0x3fb8aa3b, v49
	v_exp_f32_e32 v49, v49
	v_lshlrev_b32_e32 v35, 16, v33
	v_mov_b32_e32 v51, v35
	v_add_f32_e32 v48, v48, v48
	v_add_f32_e32 v49, 1.0, v49
	v_rcp_f32_e32 v50, v49
	v_mul_f32_e32 v49, 0x3d372713, v35
	v_mul_f32_e32 v49, v49, v35
	v_fmac_f32_e32 v51, v49, v51
	v_mul_f32_e32 v49, 0x3f4c422a, v51
	v_add_f32_e32 v49, v49, v49
	v_mul_f32_e32 v48, 0x3fb8aa3b, v48
	v_mul_f32_e32 v49, 0x3fb8aa3b, v49
	v_exp_f32_e32 v48, v48
	v_exp_f32_e32 v49, v49
	v_and_b32_e32 v33, 0xffff0000, v33
	v_pk_mul_f32 v[34:35], v[34:35], 0.5 op_sel_hi:[1,0]
	v_add_f32_e32 v48, 1.0, v48
	v_add_f32_e32 v49, 1.0, v49
	v_rcp_f32_e32 v48, v48
	v_rcp_f32_e32 v49, v49
	s_nop 0
	v_pk_fma_f32 v[48:49], v[48:49], 2.0, 1.0 op_sel_hi:[1,0,0] neg_lo:[1,0,0] neg_hi:[1,0,0]
	s_nop 0
	v_pk_add_f32 v[48:49], v[48:49], 1.0 op_sel_hi:[1,0]
	s_nop 0
	v_pk_mul_f32 v[34:35], v[34:35], v[48:49]
	v_mov_b32_e32 v48, v36
	v_mul_f32_e32 v36, 0x3d372713, v33
	v_mov_b32_e32 v49, v38
	v_mul_f32_e32 v36, v36, v33
	v_mov_b32_e32 v38, v33
	v_fmac_f32_e32 v38, v36, v38
	v_mul_f32_e32 v36, 0x3f4c422a, v38
	v_add_f32_e32 v36, v36, v36
	v_mul_f32_e32 v36, 0x3fb8aa3b, v36
	v_exp_f32_e32 v36, v36
	v_pk_add_f32 v[48:49], v[48:49], v[64:65] op_sel_hi:[1,0]
	v_pk_mul_f32 v[32:33], v[32:33], 0.5 op_sel_hi:[1,0]
	v_pk_mul_f32 v[34:35], v[48:49], v[34:35]
	v_add_f32_e32 v36, 1.0, v36
	v_rcp_f32_e32 v51, v36
	v_mov_b32_e32 v38, v37
	v_pk_add_f32 v[36:37], v[38:39], v[64:65] op_sel_hi:[1,0]
	v_pk_fma_f32 v[48:49], v[50:51], 2.0, 1.0 op_sel_hi:[1,0,0] neg_lo:[1,0,0] neg_hi:[1,0,0]
	s_nop 0
	v_pk_add_f32 v[48:49], v[48:49], 1.0 op_sel_hi:[1,0]
	s_nop 0
	v_pk_mul_f32 v[32:33], v[32:33], v[48:49]
	s_nop 0
	v_pk_mul_f32 v[32:33], v[36:37], v[32:33]
	v_and_b32_sdwa v36, v35, v196 dst_sel:DWORD dst_unused:UNUSED_PAD src0_sel:WORD_1 src1_sel:DWORD
	v_and_b32_sdwa v37, v34, v196 dst_sel:DWORD dst_unused:UNUSED_PAD src0_sel:WORD_1 src1_sel:DWORD
	s_nop 0
	v_add3_u32 v34, v34, v37, s45
	v_add3_u32 v35, v35, v36, s45
	v_and_b32_sdwa v36, v33, v196 dst_sel:DWORD dst_unused:UNUSED_PAD src0_sel:WORD_1 src1_sel:DWORD
	v_and_b32_sdwa v37, v32, v196 dst_sel:DWORD dst_unused:UNUSED_PAD src0_sel:WORD_1 src1_sel:DWORD
	v_add3_u32 v33, v33, v36, s45
	v_add3_u32 v32, v32, v37, s45
	v_and_b32_e32 v33, 0xffff0000, v33
	v_and_b32_e32 v32, 0xffff0000, v32
	v_or_b32_sdwa v33, v33, v35 dst_sel:DWORD dst_unused:UNUSED_PAD src0_sel:DWORD src1_sel:WORD_1
	v_or_b32_sdwa v32, v32, v34 dst_sel:DWORD dst_unused:UNUSED_PAD src0_sel:DWORD src1_sel:WORD_1
	global_store_dwordx2 v[66:67], v[32:33], off offset:80
	s_waitcnt vmcnt(15)
; __device__ __forceinline__ unsigned pk2(float lo, float hi) { return f2bf(lo) | (f2bf(hi) << 16); }
; __device__ __forceinline__ float gelu_tanh(float x) {
;     const float u = 0.7978845608028654f * (x + 0.044715f * x * x * x);
;     const float e = __expf(2.0f * u);
;     const float th = 1.0f - 2.0f * __builtin_amdgcn_rcpf(e + 1.0f);
;     return 0.5f * x * (1.0f + th);
; }
; __device__ __forceinline__ void gmlp_fast(KArgs ap, int l, LAS unsigned char* lds, const Ctx cx) {
;     ...
; #pragma unroll
;             for (int ht = 0; ht < 4; ++ht)
; #pragma unroll
;                 for (int q4 = 0; q4 < 4; ++q4) { const u32x2 uu = *(const u32x2*)(zu + ht * 32 + 8 * q4);
;                     const float o0 = gelu_tanh(bflo(uu.x)) * (acc[ht][4 * q4] + bsv), o1 = gelu_tanh(bfhi(uu.x)) * (acc[ht][4 * q4 + 1] + bsv);
;                     const float o2 = gelu_tanh(bflo(uu.y)) * (acc[ht][4 * q4 + 2] + bsv), o3 = gelu_tanh(bfhi(uu.y)) * (acc[ht][4 * q4 + 3] + bsv);
;                     u32x2 w; w.x = pk2(o0, o1); w.y = pk2(o2, o3); *(u32x2*)(yo + ht * 32 + 8 * q4) = w; }
	v_mov_b32_e32 v32, v210
	v_mov_b32_e32 v33, v211
	v_lshlrev_b32_e32 v34, 16, v32
	v_mul_f32_e32 v36, 0x3d372713, v34
	v_mul_f32_e32 v36, v36, v34
	v_mov_b32_e32 v37, v34
	v_fmac_f32_e32 v37, v36, v37
	v_and_b32_e32 v32, 0xffff0000, v32
	v_mul_f32_e32 v36, 0x3f4c422a, v37
	v_mul_f32_e32 v37, 0x3d372713, v32
	v_mul_f32_e32 v37, v37, v32
	v_mov_b32_e32 v38, v32
	v_fmac_f32_e32 v38, v37, v38
	v_mul_f32_e32 v37, 0x3f4c422a, v38
	v_add_f32_e32 v37, v37, v37
	v_mul_f32_e32 v37, 0x3fb8aa3b, v37
	v_exp_f32_e32 v37, v37
	v_lshlrev_b32_e32 v35, 16, v33
	v_mov_b32_e32 v39, v35
	v_add_f32_e32 v36, v36, v36
	v_add_f32_e32 v37, 1.0, v37
	v_rcp_f32_e32 v38, v37
	v_mul_f32_e32 v37, 0x3d372713, v35
	v_mul_f32_e32 v37, v37, v35
	v_fmac_f32_e32 v39, v37, v39
	v_mul_f32_e32 v37, 0x3f4c422a, v39
	v_add_f32_e32 v37, v37, v37
	v_mul_f32_e32 v36, 0x3fb8aa3b, v36
	v_mul_f32_e32 v37, 0x3fb8aa3b, v37
	v_exp_f32_e32 v36, v36
	v_exp_f32_e32 v37, v37
	v_pk_mul_f32 v[34:35], v[34:35], 0.5 op_sel_hi:[1,0]
	v_and_b32_e32 v33, 0xffff0000, v33
	v_add_f32_e32 v36, 1.0, v36
	v_add_f32_e32 v37, 1.0, v37
	v_rcp_f32_e32 v36, v36
	v_rcp_f32_e32 v37, v37
	s_nop 0
	v_pk_fma_f32 v[36:37], v[36:37], 2.0, 1.0 op_sel_hi:[1,0,0] neg_lo:[1,0,0] neg_hi:[1,0,0]
	s_nop 0
	v_pk_add_f32 v[36:37], v[36:37], 1.0 op_sel_hi:[1,0]
	s_nop 0
	v_pk_mul_f32 v[34:35], v[34:35], v[36:37]
	v_mov_b32_e32 v36, v40
	v_mov_b32_e32 v37, v42
	v_pk_add_f32 v[36:37], v[36:37], v[64:65] op_sel_hi:[1,0]
	v_mov_b32_e32 v42, v41
	v_pk_mul_f32 v[34:35], v[36:37], v[34:35]
	v_mul_f32_e32 v36, 0x3d372713, v33
	v_mul_f32_e32 v36, v36, v33
	v_mov_b32_e32 v37, v33
	v_fmac_f32_e32 v37, v36, v37
	v_mul_f32_e32 v36, 0x3f4c422a, v37
	v_add_f32_e32 v36, v36, v36
	v_mul_f32_e32 v36, 0x3fb8aa3b, v36
	v_exp_f32_e32 v36, v36
	v_pk_mul_f32 v[32:33], v[32:33], 0.5 op_sel_hi:[1,0]
	v_add_f32_e32 v36, 1.0, v36
	v_rcp_f32_e32 v39, v36
	s_nop 0
	v_pk_fma_f32 v[36:37], v[38:39], 2.0, 1.0 op_sel_hi:[1,0,0] neg_lo:[1,0,0] neg_hi:[1,0,0]
	s_nop 0
	v_pk_add_f32 v[36:37], v[36:37], 1.0 op_sel_hi:[1,0]
	s_nop 0
	v_pk_mul_f32 v[32:33], v[32:33], v[36:37]
	v_pk_add_f32 v[36:37], v[42:43], v[64:65] op_sel_hi:[1,0]
	s_nop 0
	v_pk_mul_f32 v[32:33], v[36:37], v[32:33]
	v_and_b32_sdwa v36, v35, v196 dst_sel:DWORD dst_unused:UNUSED_PAD src0_sel:WORD_1 src1_sel:DWORD
	v_and_b32_sdwa v37, v34, v196 dst_sel:DWORD dst_unused:UNUSED_PAD src0_sel:WORD_1 src1_sel:DWORD
	s_nop 0
	v_add3_u32 v34, v34, v37, s45
	v_add3_u32 v35, v35, v36, s45
	v_and_b32_sdwa v36, v33, v196 dst_sel:DWORD dst_unused:UNUSED_PAD src0_sel:WORD_1 src1_sel:DWORD
	v_and_b32_sdwa v37, v32, v196 dst_sel:DWORD dst_unused:UNUSED_PAD src0_sel:WORD_1 src1_sel:DWORD
	v_add3_u32 v33, v33, v36, s45
	v_add3_u32 v32, v32, v37, s45
	v_and_b32_e32 v33, 0xffff0000, v33
	v_and_b32_e32 v32, 0xffff0000, v32
	v_or_b32_sdwa v33, v33, v35 dst_sel:DWORD dst_unused:UNUSED_PAD src0_sel:DWORD src1_sel:WORD_1
	v_or_b32_sdwa v32, v32, v34 dst_sel:DWORD dst_unused:UNUSED_PAD src0_sel:DWORD src1_sel:WORD_1
	global_store_dwordx2 v[66:67], v[32:33], off offset:96
	s_waitcnt vmcnt(15)
	v_mov_b32_e32 v32, v212
	v_mov_b32_e32 v33, v213
	v_lshlrev_b32_e32 v34, 16, v32
	v_mul_f32_e32 v36, 0x3d372713, v34
	v_mul_f32_e32 v36, v36, v34
	v_mov_b32_e32 v37, v34
	v_fmac_f32_e32 v37, v36, v37
	v_and_b32_e32 v32, 0xffff0000, v32
	v_mul_f32_e32 v36, 0x3f4c422a, v37
	v_mul_f32_e32 v37, 0x3d372713, v32
	v_mul_f32_e32 v37, v37, v32
	v_mov_b32_e32 v38, v32
	v_fmac_f32_e32 v38, v37, v38
	v_mul_f32_e32 v37, 0x3f4c422a, v38
	v_add_f32_e32 v37, v37, v37
	v_mul_f32_e32 v37, 0x3fb8aa3b, v37
	v_exp_f32_e32 v37, v37
	v_lshlrev_b32_e32 v35, 16, v33
	v_mov_b32_e32 v39, v35
	v_add_f32_e32 v36, v36, v36
	v_add_f32_e32 v37, 1.0, v37
	v_rcp_f32_e32 v38, v37
	v_mul_f32_e32 v37, 0x3d372713, v35
	v_mul_f32_e32 v37, v37, v35
	v_fmac_f32_e32 v39, v37, v39
	v_mul_f32_e32 v37, 0x3f4c422a, v39
	v_add_f32_e32 v37, v37, v37
	v_mul_f32_e32 v36, 0x3fb8aa3b, v36
	v_mul_f32_e32 v37, 0x3fb8aa3b, v37
	v_exp_f32_e32 v36, v36
	v_exp_f32_e32 v37, v37
	v_pk_mul_f32 v[34:35], v[34:35], 0.5 op_sel_hi:[1,0]
	v_and_b32_e32 v33, 0xffff0000, v33
	v_add_f32_e32 v36, 1.0, v36
	v_add_f32_e32 v37, 1.0, v37
	v_rcp_f32_e32 v36, v36
	v_rcp_f32_e32 v37, v37
	s_nop 0
	v_pk_fma_f32 v[36:37], v[36:37], 2.0, 1.0 op_sel_hi:[1,0,0] neg_lo:[1,0,0] neg_hi:[1,0,0]
	s_nop 0
	v_pk_add_f32 v[36:37], v[36:37], 1.0 op_sel_hi:[1,0]
	s_nop 0
	v_pk_mul_f32 v[34:35], v[34:35], v[36:37]
	v_mov_b32_e32 v36, v44
	v_mov_b32_e32 v37, v46
	v_pk_add_f32 v[36:37], v[36:37], v[64:65] op_sel_hi:[1,0]
	v_mov_b32_e32 v46, v45
	v_pk_mul_f32 v[34:35], v[36:37], v[34:35]
	v_mul_f32_e32 v36, 0x3d372713, v33
	v_mul_f32_e32 v36, v36, v33
	v_mov_b32_e32 v37, v33
	v_fmac_f32_e32 v37, v36, v37
	v_mul_f32_e32 v36, 0x3f4c422a, v37
	v_add_f32_e32 v36, v36, v36
	v_mul_f32_e32 v36, 0x3fb8aa3b, v36
	v_exp_f32_e32 v36, v36
	v_pk_mul_f32 v[32:33], v[32:33], 0.5 op_sel_hi:[1,0]
	v_add_f32_e32 v36, 1.0, v36
	v_rcp_f32_e32 v39, v36
	s_nop 0
	v_pk_fma_f32 v[36:37], v[38:39], 2.0, 1.0 op_sel_hi:[1,0,0] neg_lo:[1,0,0] neg_hi:[1,0,0]
	s_nop 0
	v_pk_add_f32 v[36:37], v[36:37], 1.0 op_sel_hi:[1,0]
	s_nop 0
	v_pk_mul_f32 v[32:33], v[32:33], v[36:37]
	v_pk_add_f32 v[36:37], v[46:47], v[64:65] op_sel_hi:[1,0]
	s_nop 0
	v_pk_mul_f32 v[32:33], v[36:37], v[32:33]
	v_and_b32_sdwa v36, v35, v196 dst_sel:DWORD dst_unused:UNUSED_PAD src0_sel:WORD_1 src1_sel:DWORD
	v_and_b32_sdwa v37, v34, v196 dst_sel:DWORD dst_unused:UNUSED_PAD src0_sel:WORD_1 src1_sel:DWORD
	s_nop 0
	v_add3_u32 v34, v34, v37, s45
	v_add3_u32 v35, v35, v36, s45
	v_and_b32_sdwa v36, v33, v196 dst_sel:DWORD dst_unused:UNUSED_PAD src0_sel:WORD_1 src1_sel:DWORD
	v_and_b32_sdwa v37, v32, v196 dst_sel:DWORD dst_unused:UNUSED_PAD src0_sel:WORD_1 src1_sel:DWORD
	v_add3_u32 v33, v33, v36, s45
	v_add3_u32 v32, v32, v37, s45
	v_and_b32_e32 v33, 0xffff0000, v33
	v_and_b32_e32 v32, 0xffff0000, v32
	v_or_b32_sdwa v33, v33, v35 dst_sel:DWORD dst_unused:UNUSED_PAD src0_sel:DWORD src1_sel:WORD_1
	v_or_b32_sdwa v32, v32, v34 dst_sel:DWORD dst_unused:UNUSED_PAD src0_sel:DWORD src1_sel:WORD_1
	global_store_dwordx2 v[66:67], v[32:33], off offset:112
	s_waitcnt vmcnt(15)
; __device__ __forceinline__ unsigned pk2(float lo, float hi) { return f2bf(lo) | (f2bf(hi) << 16); }
; __device__ __forceinline__ float gelu_tanh(float x) {
;     const float u = 0.7978845608028654f * (x + 0.044715f * x * x * x);
;     const float e = __expf(2.0f * u);
;     const float th = 1.0f - 2.0f * __builtin_amdgcn_rcpf(e + 1.0f);
;     return 0.5f * x * (1.0f + th);
; }
; __device__ __forceinline__ void gmlp_fast(KArgs ap, int l, LAS unsigned char* lds, const Ctx cx) {
;     ...
; #pragma unroll
;             for (int ht = 0; ht < 4; ++ht)
; #pragma unroll
;                 for (int q4 = 0; q4 < 4; ++q4) { const u32x2 uu = *(const u32x2*)(zu + ht * 32 + 8 * q4);
;                     const float o0 = gelu_tanh(bflo(uu.x)) * (acc[ht][4 * q4] + bsv), o1 = gelu_tanh(bfhi(uu.x)) * (acc[ht][4 * q4 + 1] + bsv);
;                     const float o2 = gelu_tanh(bflo(uu.y)) * (acc[ht][4 * q4 + 2] + bsv), o3 = gelu_tanh(bfhi(uu.y)) * (acc[ht][4 * q4 + 3] + bsv);
;                     u32x2 w; w.x = pk2(o0, o1); w.y = pk2(o2, o3); *(u32x2*)(yo + ht * 32 + 8 * q4) = w; }
	v_mov_b32_e32 v32, v214
	v_mov_b32_e32 v33, v215
	v_lshlrev_b32_e32 v34, 16, v32
	v_mul_f32_e32 v36, 0x3d372713, v34
	v_mul_f32_e32 v36, v36, v34
	v_mov_b32_e32 v37, v34
	v_fmac_f32_e32 v37, v36, v37
	v_and_b32_e32 v32, 0xffff0000, v32
	v_mul_f32_e32 v36, 0x3f4c422a, v37
	v_mul_f32_e32 v37, 0x3d372713, v32
	v_mul_f32_e32 v37, v37, v32
	v_mov_b32_e32 v38, v32
	v_fmac_f32_e32 v38, v37, v38
	v_mul_f32_e32 v37, 0x3f4c422a, v38
	v_add_f32_e32 v37, v37, v37
	v_mul_f32_e32 v37, 0x3fb8aa3b, v37
	v_exp_f32_e32 v37, v37
	v_lshlrev_b32_e32 v35, 16, v33
	v_mov_b32_e32 v39, v35
	v_add_f32_e32 v36, v36, v36
	v_add_f32_e32 v37, 1.0, v37
	v_rcp_f32_e32 v38, v37
	v_mul_f32_e32 v37, 0x3d372713, v35
	v_mul_f32_e32 v37, v37, v35
	v_fmac_f32_e32 v39, v37, v39
	v_mul_f32_e32 v37, 0x3f4c422a, v39
	v_add_f32_e32 v37, v37, v37
	v_mul_f32_e32 v36, 0x3fb8aa3b, v36
	v_mul_f32_e32 v37, 0x3fb8aa3b, v37
	v_exp_f32_e32 v36, v36
	v_exp_f32_e32 v37, v37
	v_and_b32_e32 v33, 0xffff0000, v33
	v_pk_mul_f32 v[34:35], v[34:35], 0.5 op_sel_hi:[1,0]
	v_add_f32_e32 v36, 1.0, v36
	v_add_f32_e32 v37, 1.0, v37
	v_rcp_f32_e32 v36, v36
	v_rcp_f32_e32 v37, v37
	s_nop 0
	v_pk_fma_f32 v[36:37], v[36:37], 2.0, 1.0 op_sel_hi:[1,0,0] neg_lo:[1,0,0] neg_hi:[1,0,0]
	s_nop 0
	v_pk_add_f32 v[36:37], v[36:37], 1.0 op_sel_hi:[1,0]
	s_nop 0
	v_pk_mul_f32 v[34:35], v[34:35], v[36:37]
	v_mov_b32_e32 v36, v16
	v_mul_f32_e32 v16, 0x3d372713, v33
	v_mov_b32_e32 v37, v18
	v_mul_f32_e32 v16, v16, v33
	v_mov_b32_e32 v18, v33
	v_fmac_f32_e32 v18, v16, v18
	v_mul_f32_e32 v16, 0x3f4c422a, v18
	v_add_f32_e32 v16, v16, v16
	v_mul_f32_e32 v16, 0x3fb8aa3b, v16
	v_exp_f32_e32 v16, v16
	v_pk_add_f32 v[36:37], v[36:37], v[64:65] op_sel_hi:[1,0]
	v_pk_mul_f32 v[32:33], v[32:33], 0.5 op_sel_hi:[1,0]
	v_pk_mul_f32 v[34:35], v[36:37], v[34:35]
	v_add_f32_e32 v16, 1.0, v16
	v_rcp_f32_e32 v39, v16
	v_mov_b32_e32 v18, v17
	v_pk_add_f32 v[16:17], v[18:19], v[64:65] op_sel_hi:[1,0]
	v_pk_fma_f32 v[36:37], v[38:39], 2.0, 1.0 op_sel_hi:[1,0,0] neg_lo:[1,0,0] neg_hi:[1,0,0]
	s_nop 0
	v_pk_add_f32 v[36:37], v[36:37], 1.0 op_sel_hi:[1,0]
	s_nop 0
	v_pk_mul_f32 v[32:33], v[32:33], v[36:37]
	s_nop 0
	v_pk_mul_f32 v[16:17], v[16:17], v[32:33]
	s_nop 0
	v_cvt_pk_bf16_f32 v17, v35, v17
	v_cvt_pk_bf16_f32 v16, v34, v16
	global_store_dwordx2 v[66:67], v[16:17], off offset:128
	s_waitcnt vmcnt(15)
	v_mov_b32_e32 v16, v216
	v_mov_b32_e32 v17, v217
	v_lshlrev_b32_e32 v18, 16, v16
	v_mul_f32_e32 v32, 0x3d372713, v18
	v_mul_f32_e32 v32, v32, v18
	v_mov_b32_e32 v33, v18
	v_fmac_f32_e32 v33, v32, v33
	v_and_b32_e32 v16, 0xffff0000, v16
	v_mul_f32_e32 v32, 0x3f4c422a, v33
	v_mul_f32_e32 v33, 0x3d372713, v16
	v_mul_f32_e32 v33, v33, v16
	v_mov_b32_e32 v34, v16
	v_fmac_f32_e32 v34, v33, v34
	v_mul_f32_e32 v33, 0x3f4c422a, v34
	v_add_f32_e32 v33, v33, v33
	v_mul_f32_e32 v33, 0x3fb8aa3b, v33
	v_exp_f32_e32 v33, v33
	v_lshlrev_b32_e32 v19, 16, v17
	v_mov_b32_e32 v35, v19
	v_add_f32_e32 v32, v32, v32
	v_add_f32_e32 v33, 1.0, v33
	v_rcp_f32_e32 v34, v33
	v_mul_f32_e32 v33, 0x3d372713, v19
	v_mul_f32_e32 v33, v33, v19
	v_fmac_f32_e32 v35, v33, v35
	v_mul_f32_e32 v33, 0x3f4c422a, v35
	v_add_f32_e32 v33, v33, v33
	v_mul_f32_e32 v32, 0x3fb8aa3b, v32
	v_mul_f32_e32 v33, 0x3fb8aa3b, v33
	v_exp_f32_e32 v32, v32
	v_exp_f32_e32 v33, v33
	v_and_b32_e32 v17, 0xffff0000, v17
	v_pk_mul_f32 v[18:19], v[18:19], 0.5 op_sel_hi:[1,0]
	v_add_f32_e32 v32, 1.0, v32
	v_add_f32_e32 v33, 1.0, v33
	v_rcp_f32_e32 v32, v32
	v_rcp_f32_e32 v33, v33
	s_nop 0
	v_pk_fma_f32 v[32:33], v[32:33], 2.0, 1.0 op_sel_hi:[1,0,0] neg_lo:[1,0,0] neg_hi:[1,0,0]
	s_nop 0
	v_pk_add_f32 v[32:33], v[32:33], 1.0 op_sel_hi:[1,0]
	s_nop 0
	v_pk_mul_f32 v[18:19], v[18:19], v[32:33]
	v_mov_b32_e32 v32, v20
	v_mul_f32_e32 v20, 0x3d372713, v17
	v_mov_b32_e32 v33, v22
	v_mul_f32_e32 v20, v20, v17
	v_mov_b32_e32 v22, v17
	v_fmac_f32_e32 v22, v20, v22
	v_mul_f32_e32 v20, 0x3f4c422a, v22
	v_add_f32_e32 v20, v20, v20
	v_mul_f32_e32 v20, 0x3fb8aa3b, v20
	v_exp_f32_e32 v20, v20
	v_pk_add_f32 v[32:33], v[32:33], v[64:65] op_sel_hi:[1,0]
	v_pk_mul_f32 v[16:17], v[16:17], 0.5 op_sel_hi:[1,0]
	v_pk_mul_f32 v[18:19], v[32:33], v[18:19]
	v_add_f32_e32 v20, 1.0, v20
	v_rcp_f32_e32 v35, v20
	v_mov_b32_e32 v22, v21
	v_pk_add_f32 v[20:21], v[22:23], v[64:65] op_sel_hi:[1,0]
	v_pk_fma_f32 v[32:33], v[34:35], 2.0, 1.0 op_sel_hi:[1,0,0] neg_lo:[1,0,0] neg_hi:[1,0,0]
	s_nop 0
	v_pk_add_f32 v[32:33], v[32:33], 1.0 op_sel_hi:[1,0]
	s_nop 0
	v_pk_mul_f32 v[16:17], v[16:17], v[32:33]
	s_nop 0
	v_pk_mul_f32 v[16:17], v[20:21], v[16:17]
	v_and_b32_sdwa v20, v19, v196 dst_sel:DWORD dst_unused:UNUSED_PAD src0_sel:WORD_1 src1_sel:DWORD
	v_and_b32_sdwa v21, v18, v196 dst_sel:DWORD dst_unused:UNUSED_PAD src0_sel:WORD_1 src1_sel:DWORD
	s_nop 0
	v_add3_u32 v18, v18, v21, s45
	v_add3_u32 v19, v19, v20, s45
	v_and_b32_sdwa v20, v17, v196 dst_sel:DWORD dst_unused:UNUSED_PAD src0_sel:WORD_1 src1_sel:DWORD
	v_and_b32_sdwa v21, v16, v196 dst_sel:DWORD dst_unused:UNUSED_PAD src0_sel:WORD_1 src1_sel:DWORD
	v_add3_u32 v17, v17, v20, s45
	v_add3_u32 v16, v16, v21, s45
	v_and_b32_e32 v17, 0xffff0000, v17
	v_and_b32_e32 v16, 0xffff0000, v16
	v_or_b32_sdwa v17, v17, v19 dst_sel:DWORD dst_unused:UNUSED_PAD src0_sel:DWORD src1_sel:WORD_1
	v_or_b32_sdwa v16, v16, v18 dst_sel:DWORD dst_unused:UNUSED_PAD src0_sel:DWORD src1_sel:WORD_1
	global_store_dwordx2 v[66:67], v[16:17], off offset:144
	s_waitcnt vmcnt(15)
; __device__ __forceinline__ unsigned pk2(float lo, float hi) { return f2bf(lo) | (f2bf(hi) << 16); }
; __device__ __forceinline__ float gelu_tanh(float x) {
;     const float u = 0.7978845608028654f * (x + 0.044715f * x * x * x);
;     const float e = __expf(2.0f * u);
;     const float th = 1.0f - 2.0f * __builtin_amdgcn_rcpf(e + 1.0f);
;     return 0.5f * x * (1.0f + th);
; }
; __device__ __forceinline__ void gmlp_fast(KArgs ap, int l, LAS unsigned char* lds, const Ctx cx) {
;     ...
; #pragma unroll
;             for (int ht = 0; ht < 4; ++ht)
; #pragma unroll
;                 for (int q4 = 0; q4 < 4; ++q4) { const u32x2 uu = *(const u32x2*)(zu + ht * 32 + 8 * q4);
;                     const float o0 = gelu_tanh(bflo(uu.x)) * (acc[ht][4 * q4] + bsv), o1 = gelu_tanh(bfhi(uu.x)) * (acc[ht][4 * q4 + 1] + bsv);
;                     const float o2 = gelu_tanh(bflo(uu.y)) * (acc[ht][4 * q4 + 2] + bsv), o3 = gelu_tanh(bfhi(uu.y)) * (acc[ht][4 * q4 + 3] + bsv);
;                     u32x2 w; w.x = pk2(o0, o1); w.y = pk2(o2, o3); *(u32x2*)(yo + ht * 32 + 8 * q4) = w; }
	v_mov_b32_e32 v16, v218
	v_mov_b32_e32 v17, v219
	v_lshlrev_b32_e32 v18, 16, v16
	v_mul_f32_e32 v20, 0x3d372713, v18
	v_mul_f32_e32 v20, v20, v18
	v_mov_b32_e32 v21, v18
	v_fmac_f32_e32 v21, v20, v21
	v_and_b32_e32 v16, 0xffff0000, v16
	v_mul_f32_e32 v20, 0x3f4c422a, v21
	v_mul_f32_e32 v21, 0x3d372713, v16
	v_mul_f32_e32 v21, v21, v16
	v_mov_b32_e32 v22, v16
	v_fmac_f32_e32 v22, v21, v22
	v_mul_f32_e32 v21, 0x3f4c422a, v22
	v_add_f32_e32 v21, v21, v21
	v_mul_f32_e32 v21, 0x3fb8aa3b, v21
	v_exp_f32_e32 v21, v21
	v_lshlrev_b32_e32 v19, 16, v17
	v_mov_b32_e32 v23, v19
	v_add_f32_e32 v20, v20, v20
	v_add_f32_e32 v21, 1.0, v21
	v_rcp_f32_e32 v22, v21
	v_mul_f32_e32 v21, 0x3d372713, v19
	v_mul_f32_e32 v21, v21, v19
	v_fmac_f32_e32 v23, v21, v23
	v_mul_f32_e32 v21, 0x3f4c422a, v23
	v_add_f32_e32 v21, v21, v21
	v_mul_f32_e32 v20, 0x3fb8aa3b, v20
	v_mul_f32_e32 v21, 0x3fb8aa3b, v21
	v_exp_f32_e32 v20, v20
	v_exp_f32_e32 v21, v21
	v_pk_mul_f32 v[18:19], v[18:19], 0.5 op_sel_hi:[1,0]
	v_and_b32_e32 v17, 0xffff0000, v17
	v_add_f32_e32 v20, 1.0, v20
	v_add_f32_e32 v21, 1.0, v21
	v_rcp_f32_e32 v20, v20
	v_rcp_f32_e32 v21, v21
	s_nop 0
	v_pk_fma_f32 v[20:21], v[20:21], 2.0, 1.0 op_sel_hi:[1,0,0] neg_lo:[1,0,0] neg_hi:[1,0,0]
	s_nop 0
	v_pk_add_f32 v[20:21], v[20:21], 1.0 op_sel_hi:[1,0]
	s_nop 0
	v_pk_mul_f32 v[18:19], v[18:19], v[20:21]
	v_mov_b32_e32 v20, v24
	v_mov_b32_e32 v21, v26
	v_pk_add_f32 v[20:21], v[20:21], v[64:65] op_sel_hi:[1,0]
	v_mov_b32_e32 v26, v25
	v_pk_mul_f32 v[18:19], v[20:21], v[18:19]
	v_mul_f32_e32 v20, 0x3d372713, v17
	v_mul_f32_e32 v20, v20, v17
	v_mov_b32_e32 v21, v17
	v_fmac_f32_e32 v21, v20, v21
	v_mul_f32_e32 v20, 0x3f4c422a, v21
	v_add_f32_e32 v20, v20, v20
	v_mul_f32_e32 v20, 0x3fb8aa3b, v20
	v_exp_f32_e32 v20, v20
	v_pk_mul_f32 v[16:17], v[16:17], 0.5 op_sel_hi:[1,0]
	v_add_f32_e32 v20, 1.0, v20
	v_rcp_f32_e32 v23, v20
	s_nop 0
	v_pk_fma_f32 v[20:21], v[22:23], 2.0, 1.0 op_sel_hi:[1,0,0] neg_lo:[1,0,0] neg_hi:[1,0,0]
	s_nop 0
	v_pk_add_f32 v[20:21], v[20:21], 1.0 op_sel_hi:[1,0]
	s_nop 0
	v_pk_mul_f32 v[16:17], v[16:17], v[20:21]
	v_pk_add_f32 v[20:21], v[26:27], v[64:65] op_sel_hi:[1,0]
	s_nop 0
	v_pk_mul_f32 v[16:17], v[20:21], v[16:17]
	v_and_b32_sdwa v20, v19, v196 dst_sel:DWORD dst_unused:UNUSED_PAD src0_sel:WORD_1 src1_sel:DWORD
	v_and_b32_sdwa v21, v18, v196 dst_sel:DWORD dst_unused:UNUSED_PAD src0_sel:WORD_1 src1_sel:DWORD
	s_nop 0
	v_add3_u32 v18, v18, v21, s45
	v_add3_u32 v19, v19, v20, s45
	v_and_b32_sdwa v20, v17, v196 dst_sel:DWORD dst_unused:UNUSED_PAD src0_sel:WORD_1 src1_sel:DWORD
	v_and_b32_sdwa v21, v16, v196 dst_sel:DWORD dst_unused:UNUSED_PAD src0_sel:WORD_1 src1_sel:DWORD
	v_add3_u32 v17, v17, v20, s45
	v_add3_u32 v16, v16, v21, s45
	v_and_b32_e32 v17, 0xffff0000, v17
	v_and_b32_e32 v16, 0xffff0000, v16
	v_or_b32_sdwa v17, v17, v19 dst_sel:DWORD dst_unused:UNUSED_PAD src0_sel:DWORD src1_sel:WORD_1
	v_or_b32_sdwa v16, v16, v18 dst_sel:DWORD dst_unused:UNUSED_PAD src0_sel:DWORD src1_sel:WORD_1
	global_store_dwordx2 v[66:67], v[16:17], off offset:160
	s_waitcnt vmcnt(15)
	v_mov_b32_e32 v16, v220
	v_mov_b32_e32 v17, v221
	v_lshlrev_b32_e32 v18, 16, v16
	v_mul_f32_e32 v20, 0x3d372713, v18
	v_mul_f32_e32 v20, v20, v18
	v_mov_b32_e32 v21, v18
	v_fmac_f32_e32 v21, v20, v21
	v_and_b32_e32 v16, 0xffff0000, v16
	v_mul_f32_e32 v20, 0x3f4c422a, v21
	v_mul_f32_e32 v21, 0x3d372713, v16
	v_mul_f32_e32 v21, v21, v16
	v_mov_b32_e32 v22, v16
	v_fmac_f32_e32 v22, v21, v22
	v_mul_f32_e32 v21, 0x3f4c422a, v22
	v_add_f32_e32 v21, v21, v21
	v_mul_f32_e32 v21, 0x3fb8aa3b, v21
	v_exp_f32_e32 v21, v21
	v_lshlrev_b32_e32 v19, 16, v17
	v_mov_b32_e32 v23, v19
	v_add_f32_e32 v20, v20, v20
	v_add_f32_e32 v21, 1.0, v21
	v_rcp_f32_e32 v22, v21
	v_mul_f32_e32 v21, 0x3d372713, v19
	v_mul_f32_e32 v21, v21, v19
	v_fmac_f32_e32 v23, v21, v23
	v_mul_f32_e32 v21, 0x3f4c422a, v23
	v_add_f32_e32 v21, v21, v21
	v_mul_f32_e32 v20, 0x3fb8aa3b, v20
	v_mul_f32_e32 v21, 0x3fb8aa3b, v21
	v_exp_f32_e32 v20, v20
	v_exp_f32_e32 v21, v21
	v_pk_mul_f32 v[18:19], v[18:19], 0.5 op_sel_hi:[1,0]
	v_and_b32_e32 v17, 0xffff0000, v17
	v_add_f32_e32 v20, 1.0, v20
	v_add_f32_e32 v21, 1.0, v21
	v_rcp_f32_e32 v20, v20
	v_rcp_f32_e32 v21, v21
	s_nop 0
	v_pk_fma_f32 v[20:21], v[20:21], 2.0, 1.0 op_sel_hi:[1,0,0] neg_lo:[1,0,0] neg_hi:[1,0,0]
	s_nop 0
	v_pk_add_f32 v[20:21], v[20:21], 1.0 op_sel_hi:[1,0]
	s_nop 0
	v_pk_mul_f32 v[18:19], v[18:19], v[20:21]
	v_mov_b32_e32 v20, v28
	v_mov_b32_e32 v21, v30
	v_pk_add_f32 v[20:21], v[20:21], v[64:65] op_sel_hi:[1,0]
	v_mov_b32_e32 v30, v29
	v_pk_mul_f32 v[18:19], v[20:21], v[18:19]
	v_mul_f32_e32 v20, 0x3d372713, v17
	v_mul_f32_e32 v20, v20, v17
	v_mov_b32_e32 v21, v17
	v_fmac_f32_e32 v21, v20, v21
	v_mul_f32_e32 v20, 0x3f4c422a, v21
	v_add_f32_e32 v20, v20, v20
	v_mul_f32_e32 v20, 0x3fb8aa3b, v20
	v_exp_f32_e32 v20, v20
	v_pk_mul_f32 v[16:17], v[16:17], 0.5 op_sel_hi:[1,0]
	v_add_f32_e32 v20, 1.0, v20
	v_rcp_f32_e32 v23, v20
	s_nop 0
	v_pk_fma_f32 v[20:21], v[22:23], 2.0, 1.0 op_sel_hi:[1,0,0] neg_lo:[1,0,0] neg_hi:[1,0,0]
	s_nop 0
	v_pk_add_f32 v[20:21], v[20:21], 1.0 op_sel_hi:[1,0]
	s_nop 0
	v_pk_mul_f32 v[16:17], v[16:17], v[20:21]
	v_pk_add_f32 v[20:21], v[30:31], v[64:65] op_sel_hi:[1,0]
	s_nop 0
	v_pk_mul_f32 v[16:17], v[20:21], v[16:17]
	v_and_b32_sdwa v20, v19, v196 dst_sel:DWORD dst_unused:UNUSED_PAD src0_sel:WORD_1 src1_sel:DWORD
	v_and_b32_sdwa v21, v18, v196 dst_sel:DWORD dst_unused:UNUSED_PAD src0_sel:WORD_1 src1_sel:DWORD
	s_nop 0
	v_add3_u32 v18, v18, v21, s45
	v_add3_u32 v19, v19, v20, s45
	v_and_b32_sdwa v20, v17, v196 dst_sel:DWORD dst_unused:UNUSED_PAD src0_sel:WORD_1 src1_sel:DWORD
	v_and_b32_sdwa v21, v16, v196 dst_sel:DWORD dst_unused:UNUSED_PAD src0_sel:WORD_1 src1_sel:DWORD
	v_add3_u32 v17, v17, v20, s45
	v_add3_u32 v16, v16, v21, s45
	v_and_b32_e32 v17, 0xffff0000, v17
	v_and_b32_e32 v16, 0xffff0000, v16
	v_or_b32_sdwa v17, v17, v19 dst_sel:DWORD dst_unused:UNUSED_PAD src0_sel:DWORD src1_sel:WORD_1
	v_or_b32_sdwa v16, v16, v18 dst_sel:DWORD dst_unused:UNUSED_PAD src0_sel:DWORD src1_sel:WORD_1
	global_store_dwordx2 v[66:67], v[16:17], off offset:176
	s_waitcnt vmcnt(15)
; __device__ __forceinline__ unsigned pk2(float lo, float hi) { return f2bf(lo) | (f2bf(hi) << 16); }
; __device__ __forceinline__ float gelu_tanh(float x) {
;     const float u = 0.7978845608028654f * (x + 0.044715f * x * x * x);
;     const float e = __expf(2.0f * u);
;     const float th = 1.0f - 2.0f * __builtin_amdgcn_rcpf(e + 1.0f);
;     return 0.5f * x * (1.0f + th);
; }
; __device__ __forceinline__ void gmlp_fast(KArgs ap, int l, LAS unsigned char* lds, const Ctx cx) {
;     ...
; #pragma unroll
;             for (int ht = 0; ht < 4; ++ht)
; #pragma unroll
;                 for (int q4 = 0; q4 < 4; ++q4) { const u32x2 uu = *(const u32x2*)(zu + ht * 32 + 8 * q4);
;                     const float o0 = gelu_tanh(bflo(uu.x)) * (acc[ht][4 * q4] + bsv), o1 = gelu_tanh(bfhi(uu.x)) * (acc[ht][4 * q4 + 1] + bsv);
;                     const float o2 = gelu_tanh(bflo(uu.y)) * (acc[ht][4 * q4 + 2] + bsv), o3 = gelu_tanh(bfhi(uu.y)) * (acc[ht][4 * q4 + 3] + bsv);
;                     u32x2 w; w.x = pk2(o0, o1); w.y = pk2(o2, o3); *(u32x2*)(yo + ht * 32 + 8 * q4) = w; }
	v_mov_b32_e32 v16, v222
	v_mov_b32_e32 v17, v223
	v_lshlrev_b32_e32 v18, 16, v16
	v_mul_f32_e32 v20, 0x3d372713, v18
	v_mul_f32_e32 v20, v20, v18
	v_mov_b32_e32 v21, v18
	v_fmac_f32_e32 v21, v20, v21
	v_and_b32_e32 v16, 0xffff0000, v16
	v_mul_f32_e32 v20, 0x3f4c422a, v21
	v_mul_f32_e32 v21, 0x3d372713, v16
	v_mul_f32_e32 v21, v21, v16
	v_mov_b32_e32 v22, v16
	v_fmac_f32_e32 v22, v21, v22
	v_mul_f32_e32 v21, 0x3f4c422a, v22
	v_add_f32_e32 v21, v21, v21
	v_mul_f32_e32 v21, 0x3fb8aa3b, v21
	v_exp_f32_e32 v21, v21
	v_lshlrev_b32_e32 v19, 16, v17
	v_mov_b32_e32 v23, v19
	v_add_f32_e32 v20, v20, v20
	v_add_f32_e32 v21, 1.0, v21
	v_rcp_f32_e32 v22, v21
	v_mul_f32_e32 v21, 0x3d372713, v19
	v_mul_f32_e32 v21, v21, v19
	v_fmac_f32_e32 v23, v21, v23
	v_mul_f32_e32 v21, 0x3f4c422a, v23
	v_add_f32_e32 v21, v21, v21
	v_mul_f32_e32 v20, 0x3fb8aa3b, v20
	v_mul_f32_e32 v21, 0x3fb8aa3b, v21
	v_exp_f32_e32 v20, v20
	v_exp_f32_e32 v21, v21
	v_and_b32_e32 v17, 0xffff0000, v17
	v_pk_mul_f32 v[18:19], v[18:19], 0.5 op_sel_hi:[1,0]
	v_add_f32_e32 v20, 1.0, v20
	v_add_f32_e32 v21, 1.0, v21
	v_rcp_f32_e32 v20, v20
	v_rcp_f32_e32 v21, v21
	s_nop 0
	v_pk_fma_f32 v[20:21], v[20:21], 2.0, 1.0 op_sel_hi:[1,0,0] neg_lo:[1,0,0] neg_hi:[1,0,0]
	s_nop 0
	v_pk_add_f32 v[20:21], v[20:21], 1.0 op_sel_hi:[1,0]
	s_nop 0
	v_pk_mul_f32 v[18:19], v[18:19], v[20:21]
	v_mov_b32_e32 v20, v0
	v_mul_f32_e32 v0, 0x3d372713, v17
	v_mov_b32_e32 v21, v2
	v_mul_f32_e32 v0, v0, v17
	v_mov_b32_e32 v2, v17
	v_fmac_f32_e32 v2, v0, v2
	v_mul_f32_e32 v0, 0x3f4c422a, v2
	v_add_f32_e32 v0, v0, v0
	v_mul_f32_e32 v0, 0x3fb8aa3b, v0
	v_exp_f32_e32 v0, v0
	v_pk_add_f32 v[20:21], v[20:21], v[64:65] op_sel_hi:[1,0]
	v_pk_mul_f32 v[16:17], v[16:17], 0.5 op_sel_hi:[1,0]
	v_pk_mul_f32 v[18:19], v[20:21], v[18:19]
	v_add_f32_e32 v0, 1.0, v0
	v_rcp_f32_e32 v23, v0
	v_mov_b32_e32 v2, v1
	v_pk_add_f32 v[0:1], v[2:3], v[64:65] op_sel_hi:[1,0]
	v_pk_fma_f32 v[20:21], v[22:23], 2.0, 1.0 op_sel_hi:[1,0,0] neg_lo:[1,0,0] neg_hi:[1,0,0]
	s_nop 0
	v_pk_add_f32 v[20:21], v[20:21], 1.0 op_sel_hi:[1,0]
	s_nop 0
	v_pk_mul_f32 v[16:17], v[16:17], v[20:21]
	s_nop 0
	v_pk_mul_f32 v[0:1], v[0:1], v[16:17]
	s_nop 0
	v_cvt_pk_bf16_f32 v1, v19, v1
	v_cvt_pk_bf16_f32 v0, v18, v0
	global_store_dwordx2 v[66:67], v[0:1], off offset:192
	s_waitcnt vmcnt(15)
	v_mov_b32_e32 v0, v224
	v_mov_b32_e32 v1, v225
	v_lshlrev_b32_e32 v2, 16, v0
	v_mul_f32_e32 v16, 0x3d372713, v2
	v_mul_f32_e32 v16, v16, v2
	v_mov_b32_e32 v17, v2
	v_fmac_f32_e32 v17, v16, v17
	v_and_b32_e32 v0, 0xffff0000, v0
	v_mul_f32_e32 v16, 0x3f4c422a, v17
	v_mul_f32_e32 v17, 0x3d372713, v0
	v_mul_f32_e32 v17, v17, v0
	v_mov_b32_e32 v18, v0
	v_fmac_f32_e32 v18, v17, v18
	v_mul_f32_e32 v17, 0x3f4c422a, v18
	v_add_f32_e32 v17, v17, v17
	v_mul_f32_e32 v17, 0x3fb8aa3b, v17
	v_exp_f32_e32 v17, v17
	v_lshlrev_b32_e32 v3, 16, v1
	v_mov_b32_e32 v19, v3
	v_add_f32_e32 v16, v16, v16
	v_add_f32_e32 v17, 1.0, v17
	v_rcp_f32_e32 v18, v17
	v_mul_f32_e32 v17, 0x3d372713, v3
	v_mul_f32_e32 v17, v17, v3
	v_fmac_f32_e32 v19, v17, v19
	v_mul_f32_e32 v17, 0x3f4c422a, v19
	v_add_f32_e32 v17, v17, v17
	v_mul_f32_e32 v16, 0x3fb8aa3b, v16
	v_mul_f32_e32 v17, 0x3fb8aa3b, v17
	v_exp_f32_e32 v16, v16
	v_exp_f32_e32 v17, v17
	v_and_b32_e32 v1, 0xffff0000, v1
	v_pk_mul_f32 v[2:3], v[2:3], 0.5 op_sel_hi:[1,0]
	v_add_f32_e32 v16, 1.0, v16
	v_add_f32_e32 v17, 1.0, v17
	v_rcp_f32_e32 v16, v16
	v_rcp_f32_e32 v17, v17
	s_nop 0
	v_pk_fma_f32 v[16:17], v[16:17], 2.0, 1.0 op_sel_hi:[1,0,0] neg_lo:[1,0,0] neg_hi:[1,0,0]
	s_nop 0
	v_pk_add_f32 v[16:17], v[16:17], 1.0 op_sel_hi:[1,0]
	s_nop 0
	v_pk_mul_f32 v[2:3], v[2:3], v[16:17]
	v_mov_b32_e32 v16, v4
	v_mul_f32_e32 v4, 0x3d372713, v1
	v_mov_b32_e32 v17, v6
	v_mul_f32_e32 v4, v4, v1
	v_mov_b32_e32 v6, v1
	v_fmac_f32_e32 v6, v4, v6
	v_mul_f32_e32 v4, 0x3f4c422a, v6
	v_add_f32_e32 v4, v4, v4
	v_mul_f32_e32 v4, 0x3fb8aa3b, v4
	v_exp_f32_e32 v4, v4
	v_pk_add_f32 v[16:17], v[16:17], v[64:65] op_sel_hi:[1,0]
	v_pk_mul_f32 v[0:1], v[0:1], 0.5 op_sel_hi:[1,0]
	v_pk_mul_f32 v[2:3], v[16:17], v[2:3]
	v_add_f32_e32 v4, 1.0, v4
	v_rcp_f32_e32 v19, v4
	v_mov_b32_e32 v6, v5
	v_pk_add_f32 v[4:5], v[6:7], v[64:65] op_sel_hi:[1,0]
	v_pk_fma_f32 v[16:17], v[18:19], 2.0, 1.0 op_sel_hi:[1,0,0] neg_lo:[1,0,0] neg_hi:[1,0,0]
	s_nop 0
	v_pk_add_f32 v[16:17], v[16:17], 1.0 op_sel_hi:[1,0]
	s_nop 0
	v_pk_mul_f32 v[0:1], v[0:1], v[16:17]
	s_nop 0
	v_pk_mul_f32 v[0:1], v[4:5], v[0:1]
	v_and_b32_sdwa v4, v3, v196 dst_sel:DWORD dst_unused:UNUSED_PAD src0_sel:WORD_1 src1_sel:DWORD
	v_and_b32_sdwa v5, v2, v196 dst_sel:DWORD dst_unused:UNUSED_PAD src0_sel:WORD_1 src1_sel:DWORD
	s_nop 0
	v_add3_u32 v2, v2, v5, s45
	v_add3_u32 v3, v3, v4, s45
	v_and_b32_sdwa v4, v1, v196 dst_sel:DWORD dst_unused:UNUSED_PAD src0_sel:WORD_1 src1_sel:DWORD
	v_and_b32_sdwa v5, v0, v196 dst_sel:DWORD dst_unused:UNUSED_PAD src0_sel:WORD_1 src1_sel:DWORD
	v_add3_u32 v1, v1, v4, s45
	v_add3_u32 v0, v0, v5, s45
	v_and_b32_e32 v1, 0xffff0000, v1
	v_and_b32_e32 v0, 0xffff0000, v0
	v_or_b32_sdwa v1, v1, v3 dst_sel:DWORD dst_unused:UNUSED_PAD src0_sel:DWORD src1_sel:WORD_1
	v_or_b32_sdwa v0, v0, v2 dst_sel:DWORD dst_unused:UNUSED_PAD src0_sel:DWORD src1_sel:WORD_1
	global_store_dwordx2 v[66:67], v[0:1], off offset:208
	s_waitcnt vmcnt(15)
; __device__ __forceinline__ unsigned pk2(float lo, float hi) { return f2bf(lo) | (f2bf(hi) << 16); }
; __device__ __forceinline__ float gelu_tanh(float x) {
;     const float u = 0.7978845608028654f * (x + 0.044715f * x * x * x);
;     const float e = __expf(2.0f * u);
;     const float th = 1.0f - 2.0f * __builtin_amdgcn_rcpf(e + 1.0f);
;     return 0.5f * x * (1.0f + th);
; }
; __device__ __forceinline__ void gmlp_fast(KArgs ap, int l, LAS unsigned char* lds, const Ctx cx) {
;     ...
; #pragma unroll
;             for (int ht = 0; ht < 4; ++ht)
; #pragma unroll
;                 for (int q4 = 0; q4 < 4; ++q4) { const u32x2 uu = *(const u32x2*)(zu + ht * 32 + 8 * q4);
;                     const float o0 = gelu_tanh(bflo(uu.x)) * (acc[ht][4 * q4] + bsv), o1 = gelu_tanh(bfhi(uu.x)) * (acc[ht][4 * q4 + 1] + bsv);
;                     const float o2 = gelu_tanh(bflo(uu.y)) * (acc[ht][4 * q4 + 2] + bsv), o3 = gelu_tanh(bfhi(uu.y)) * (acc[ht][4 * q4 + 3] + bsv);
;                     u32x2 w; w.x = pk2(o0, o1); w.y = pk2(o2, o3); *(u32x2*)(yo + ht * 32 + 8 * q4) = w; }
	v_mov_b32_e32 v0, v226
	v_mov_b32_e32 v1, v227
	v_lshlrev_b32_e32 v2, 16, v0
	v_mul_f32_e32 v4, 0x3d372713, v2
	v_mul_f32_e32 v4, v4, v2
	v_mov_b32_e32 v5, v2
	v_fmac_f32_e32 v5, v4, v5
	v_and_b32_e32 v0, 0xffff0000, v0
	v_mul_f32_e32 v4, 0x3f4c422a, v5
	v_mul_f32_e32 v5, 0x3d372713, v0
	v_mul_f32_e32 v5, v5, v0
	v_mov_b32_e32 v6, v0
	v_fmac_f32_e32 v6, v5, v6
	v_mul_f32_e32 v5, 0x3f4c422a, v6
	v_add_f32_e32 v5, v5, v5
	v_mul_f32_e32 v5, 0x3fb8aa3b, v5
	v_exp_f32_e32 v5, v5
	v_lshlrev_b32_e32 v3, 16, v1
	v_mov_b32_e32 v7, v3
	v_add_f32_e32 v4, v4, v4
	v_add_f32_e32 v5, 1.0, v5
	v_rcp_f32_e32 v6, v5
	v_mul_f32_e32 v5, 0x3d372713, v3
	v_mul_f32_e32 v5, v5, v3
	v_fmac_f32_e32 v7, v5, v7
	v_mul_f32_e32 v5, 0x3f4c422a, v7
	v_add_f32_e32 v5, v5, v5
	v_mul_f32_e32 v4, 0x3fb8aa3b, v4
	v_mul_f32_e32 v5, 0x3fb8aa3b, v5
	v_exp_f32_e32 v4, v4
	v_exp_f32_e32 v5, v5
	v_pk_mul_f32 v[2:3], v[2:3], 0.5 op_sel_hi:[1,0]
	v_and_b32_e32 v1, 0xffff0000, v1
	v_add_f32_e32 v4, 1.0, v4
	v_add_f32_e32 v5, 1.0, v5
	v_rcp_f32_e32 v4, v4
	v_rcp_f32_e32 v5, v5
	s_nop 0
	v_pk_fma_f32 v[4:5], v[4:5], 2.0, 1.0 op_sel_hi:[1,0,0] neg_lo:[1,0,0] neg_hi:[1,0,0]
	s_nop 0
	v_pk_add_f32 v[4:5], v[4:5], 1.0 op_sel_hi:[1,0]
	s_nop 0
	v_pk_mul_f32 v[2:3], v[2:3], v[4:5]
	v_mov_b32_e32 v4, v8
	v_mov_b32_e32 v5, v10
	v_pk_add_f32 v[4:5], v[4:5], v[64:65] op_sel_hi:[1,0]
	v_mov_b32_e32 v10, v9
	v_pk_mul_f32 v[2:3], v[4:5], v[2:3]
	v_mul_f32_e32 v4, 0x3d372713, v1
	v_mul_f32_e32 v4, v4, v1
	v_mov_b32_e32 v5, v1
	v_fmac_f32_e32 v5, v4, v5
	v_mul_f32_e32 v4, 0x3f4c422a, v5
	v_add_f32_e32 v4, v4, v4
	v_mul_f32_e32 v4, 0x3fb8aa3b, v4
	v_exp_f32_e32 v4, v4
	v_pk_mul_f32 v[0:1], v[0:1], 0.5 op_sel_hi:[1,0]
	v_add_f32_e32 v4, 1.0, v4
	v_rcp_f32_e32 v7, v4
	s_nop 0
	v_pk_fma_f32 v[4:5], v[6:7], 2.0, 1.0 op_sel_hi:[1,0,0] neg_lo:[1,0,0] neg_hi:[1,0,0]
	s_nop 0
	v_pk_add_f32 v[4:5], v[4:5], 1.0 op_sel_hi:[1,0]
	s_nop 0
	v_pk_mul_f32 v[0:1], v[0:1], v[4:5]
	v_pk_add_f32 v[4:5], v[10:11], v[64:65] op_sel_hi:[1,0]
	s_nop 0
	v_pk_mul_f32 v[0:1], v[4:5], v[0:1]
	v_and_b32_sdwa v4, v3, v196 dst_sel:DWORD dst_unused:UNUSED_PAD src0_sel:WORD_1 src1_sel:DWORD
	v_and_b32_sdwa v5, v2, v196 dst_sel:DWORD dst_unused:UNUSED_PAD src0_sel:WORD_1 src1_sel:DWORD
	s_nop 0
	v_add3_u32 v2, v2, v5, s45
	v_add3_u32 v3, v3, v4, s45
	v_and_b32_sdwa v4, v1, v196 dst_sel:DWORD dst_unused:UNUSED_PAD src0_sel:WORD_1 src1_sel:DWORD
	v_and_b32_sdwa v5, v0, v196 dst_sel:DWORD dst_unused:UNUSED_PAD src0_sel:WORD_1 src1_sel:DWORD
	v_add3_u32 v1, v1, v4, s45
	v_add3_u32 v0, v0, v5, s45
	v_and_b32_e32 v1, 0xffff0000, v1
	v_and_b32_e32 v0, 0xffff0000, v0
	v_or_b32_sdwa v1, v1, v3 dst_sel:DWORD dst_unused:UNUSED_PAD src0_sel:DWORD src1_sel:WORD_1
	v_or_b32_sdwa v0, v0, v2 dst_sel:DWORD dst_unused:UNUSED_PAD src0_sel:DWORD src1_sel:WORD_1
	s_nop 0
	global_store_dwordx2 v[66:67], v[0:1], off offset:224
	s_waitcnt vmcnt(15)
	v_mov_b32_e32 v2, v228
	v_mov_b32_e32 v3, v229
	v_lshlrev_b32_e32 v0, 16, v2
	v_mul_f32_e32 v4, 0x3d372713, v0
	v_mul_f32_e32 v4, v4, v0
	v_mov_b32_e32 v5, v0
	v_fmac_f32_e32 v5, v4, v5
	v_and_b32_e32 v2, 0xffff0000, v2
	v_mul_f32_e32 v4, 0x3f4c422a, v5
	v_mul_f32_e32 v5, 0x3d372713, v2
	v_mul_f32_e32 v5, v5, v2
	v_mov_b32_e32 v6, v2
	v_fmac_f32_e32 v6, v5, v6
	v_mul_f32_e32 v5, 0x3f4c422a, v6
	v_add_f32_e32 v5, v5, v5
	v_mul_f32_e32 v5, 0x3fb8aa3b, v5
	v_exp_f32_e32 v5, v5
	v_lshlrev_b32_e32 v1, 16, v3
	v_mov_b32_e32 v7, v1
	v_add_f32_e32 v4, v4, v4
	v_add_f32_e32 v5, 1.0, v5
	v_rcp_f32_e32 v6, v5
	v_mul_f32_e32 v5, 0x3d372713, v1
	v_mul_f32_e32 v5, v5, v1
	v_fmac_f32_e32 v7, v5, v7
	v_mul_f32_e32 v5, 0x3f4c422a, v7
	v_add_f32_e32 v5, v5, v5
	v_mul_f32_e32 v4, 0x3fb8aa3b, v4
	v_mul_f32_e32 v5, 0x3fb8aa3b, v5
	v_exp_f32_e32 v4, v4
	v_exp_f32_e32 v5, v5
	v_pk_mul_f32 v[0:1], v[0:1], 0.5 op_sel_hi:[1,0]
	v_and_b32_e32 v3, 0xffff0000, v3
	v_add_f32_e32 v4, 1.0, v4
	v_add_f32_e32 v5, 1.0, v5
	v_rcp_f32_e32 v4, v4
	v_rcp_f32_e32 v5, v5
	s_nop 0
	v_pk_fma_f32 v[4:5], v[4:5], 2.0, 1.0 op_sel_hi:[1,0,0] neg_lo:[1,0,0] neg_hi:[1,0,0]
	s_nop 0
	v_pk_add_f32 v[4:5], v[4:5], 1.0 op_sel_hi:[1,0]
	s_nop 0
	v_pk_mul_f32 v[0:1], v[0:1], v[4:5]
	v_mov_b32_e32 v4, v12
	v_mov_b32_e32 v5, v14
	v_pk_add_f32 v[4:5], v[4:5], v[64:65] op_sel_hi:[1,0]
	v_mov_b32_e32 v14, v13
	v_pk_mul_f32 v[0:1], v[4:5], v[0:1]
	v_mul_f32_e32 v4, 0x3d372713, v3
	v_mul_f32_e32 v4, v4, v3
	v_mov_b32_e32 v5, v3
	v_fmac_f32_e32 v5, v4, v5
	v_mul_f32_e32 v4, 0x3f4c422a, v5
	v_add_f32_e32 v4, v4, v4
	v_mul_f32_e32 v4, 0x3fb8aa3b, v4
	v_exp_f32_e32 v4, v4
	v_pk_mul_f32 v[2:3], v[2:3], 0.5 op_sel_hi:[1,0]
	v_add_f32_e32 v4, 1.0, v4
	v_rcp_f32_e32 v7, v4
	s_nop 0
	v_pk_fma_f32 v[4:5], v[6:7], 2.0, 1.0 op_sel_hi:[1,0,0] neg_lo:[1,0,0] neg_hi:[1,0,0]
	s_nop 0
	v_pk_add_f32 v[4:5], v[4:5], 1.0 op_sel_hi:[1,0]
	s_nop 0
	v_pk_mul_f32 v[2:3], v[2:3], v[4:5]
	v_pk_add_f32 v[4:5], v[14:15], v[64:65] op_sel_hi:[1,0]
	s_nop 0
	v_pk_mul_f32 v[2:3], v[4:5], v[2:3]
	v_and_b32_sdwa v4, v1, v196 dst_sel:DWORD dst_unused:UNUSED_PAD src0_sel:WORD_1 src1_sel:DWORD
	v_and_b32_sdwa v5, v0, v196 dst_sel:DWORD dst_unused:UNUSED_PAD src0_sel:WORD_1 src1_sel:DWORD
	s_nop 0
	v_add3_u32 v0, v0, v5, s45
	v_add3_u32 v1, v1, v4, s45
	v_and_b32_sdwa v4, v3, v196 dst_sel:DWORD dst_unused:UNUSED_PAD src0_sel:WORD_1 src1_sel:DWORD
	v_and_b32_sdwa v5, v2, v196 dst_sel:DWORD dst_unused:UNUSED_PAD src0_sel:WORD_1 src1_sel:DWORD
	v_add3_u32 v3, v3, v4, s45
	v_add3_u32 v2, v2, v5, s45
	v_and_b32_e32 v3, 0xffff0000, v3
	v_and_b32_e32 v2, 0xffff0000, v2
	v_or_b32_sdwa v1, v3, v1 dst_sel:DWORD dst_unused:UNUSED_PAD src0_sel:DWORD src1_sel:WORD_1
	v_or_b32_sdwa v0, v2, v0 dst_sel:DWORD dst_unused:UNUSED_PAD src0_sel:DWORD src1_sel:WORD_1
	global_store_dwordx2 v[66:67], v[0:1], off offset:240
	s_cbranch_vccnz .LBB0_140

; __device__ __forceinline__ float gelu_tanh(float x) {
;     const float u = 0.7978845608028654f * (x + 0.044715f * x * x * x);
;     const float e = __expf(2.0f * u);
;     const float th = 1.0f - 2.0f * __builtin_amdgcn_rcpf(e + 1.0f);
;     return 0.5f * x * (1.0f + th);
; }
; __device__ __forceinline__ void gmlp_fast(KArgs ap, int l, LAS unsigned char* lds, const Ctx cx) {
;     ...
;             for (int e = 0; e < 4; ++e) { const int chl = lane + 64 * e, ch = 256 * k + chl;
;                 const float gg = lng[ch], bb = lnb[ch];
;                 float vv[16];
; #pragma unroll
;                 for (int i = 0; i < 16; ++i) { const int s = wave * 16 + i; const float x = gelu_tanh(bf2f(z[(t0 + s) * DIN + ZGV + ch])); vv[i] = (x - ST[2 * s]) * ST[2 * s + 1] * gg + bb; }
.LBB0_162:
	v_lshl_add_u64 v[34:35], v[6:7], 0, s[20:21]
	global_load_dword v8, v[2:3], off offset:-256
	global_load_dword v10, v[4:5], off offset:-256
	global_load_dword v232, v[2:3], off
	global_load_dword v233, v[4:5], off
	s_add_u32 s88, s18, s20
	s_addc_u32 s89, s19, s21
	s_add_u32 s82, s88, 0x13001000
	s_addc_u32 s83, s89, 0
	global_load_ushort v200, v234, s[82:83] offset:512
	s_add_u32 s84, s88, 0x13003000
	s_addc_u32 s85, s89, 0
	global_load_ushort v201, v234, s[84:85] offset:3584
	s_add_u32 s86, s88, 0x13002000
	s_addc_u32 s87, s89, 0
	global_load_ushort v202, v234, s[86:87] offset:2048
	s_add_u32 s82, s88, 0x13005000
	s_addc_u32 s83, s89, 0
	global_load_ushort v203, v234, s[82:83] offset:1024
	s_add_u32 s84, s88, 0x13006000
	s_addc_u32 s85, s89, 0
	global_load_ushort v204, v234, s[84:85] offset:2560
	s_add_u32 s86, s88, 0x13009000
	s_addc_u32 s87, s89, 0
	global_load_ushort v205, v234, s[86:87] offset:1536
	s_add_u32 s82, s88, 0x13008000
	s_addc_u32 s83, s89, 0
	global_load_ushort v206, v234, s[82:83]
	s_add_u32 s84, s88, 0x1300a000
	s_addc_u32 s85, s89, 0
	global_load_ushort v207, v234, s[84:85] offset:3072
	s_add_u32 s86, s88, 0x1300c000
	s_addc_u32 s87, s89, 0
	global_load_ushort v208, v234, s[86:87] offset:512
	s_add_u32 s82, s88, 0x1300e000
	s_addc_u32 s83, s89, 0
	global_load_ushort v209, v234, s[82:83] offset:3584
	s_add_u32 s84, s88, 0x1300d000
	s_addc_u32 s85, s89, 0
	global_load_ushort v210, v234, s[84:85] offset:2048
	s_add_u32 s86, s88, 0x13010000
	s_addc_u32 s87, s89, 0
	global_load_ushort v211, v234, s[86:87] offset:1024
	s_add_u32 s82, s88, 0x13011000
	s_addc_u32 s83, s89, 0
	global_load_ushort v212, v234, s[82:83] offset:2560
	s_add_u32 s84, s88, 0x13014000
	s_addc_u32 s85, s89, 0
	global_load_ushort v213, v234, s[84:85] offset:1536
	s_add_u32 s86, s88, 0x13015000
	s_addc_u32 s87, s89, 0
	global_load_ushort v214, v234, s[86:87] offset:3072
	s_add_u32 s82, s88, 0x13013000
	s_addc_u32 s83, s89, 0
	global_load_ushort v215, v234, s[82:83]
	s_add_u32 s84, s88, 0x13001000
	s_addc_u32 s85, s89, 0
	global_load_ushort v216, v235, s[84:85] offset:512
	s_add_u32 s86, s88, 0x13003000
	s_addc_u32 s87, s89, 0
	global_load_ushort v217, v235, s[86:87] offset:3584
	s_add_u32 s82, s88, 0x13002000
	s_addc_u32 s83, s89, 0
	global_load_ushort v218, v235, s[82:83] offset:2048
	s_add_u32 s84, s88, 0x13005000
	s_addc_u32 s85, s89, 0
	global_load_ushort v219, v235, s[84:85] offset:1024
	s_add_u32 s86, s88, 0x13006000
	s_addc_u32 s87, s89, 0
	global_load_ushort v220, v235, s[86:87] offset:2560
	s_add_u32 s82, s88, 0x13009000
	s_addc_u32 s83, s89, 0
	global_load_ushort v221, v235, s[82:83] offset:1536
	s_add_u32 s84, s88, 0x13008000
	s_addc_u32 s85, s89, 0
	global_load_ushort v222, v235, s[84:85]
	s_add_u32 s86, s88, 0x1300a000
	s_addc_u32 s87, s89, 0
	global_load_ushort v223, v235, s[86:87] offset:3072
	s_add_u32 s82, s88, 0x1300c000
	s_addc_u32 s83, s89, 0
	global_load_ushort v224, v235, s[82:83] offset:512
	s_add_u32 s84, s88, 0x1300e000
	s_addc_u32 s85, s89, 0
	global_load_ushort v225, v235, s[84:85] offset:3584
	s_add_u32 s86, s88, 0x1300d000
	s_addc_u32 s87, s89, 0
	global_load_ushort v226, v235, s[86:87] offset:2048
	s_add_u32 s82, s88, 0x13010000
	s_addc_u32 s83, s89, 0
	global_load_ushort v227, v235, s[82:83] offset:1024
	s_add_u32 s84, s88, 0x13011000
	s_addc_u32 s85, s89, 0
	global_load_ushort v228, v235, s[84:85] offset:2560
	s_add_u32 s86, s88, 0x13014000
	s_addc_u32 s87, s89, 0
	global_load_ushort v229, v235, s[86:87] offset:1536
	s_add_u32 s82, s88, 0x13013000
	s_addc_u32 s83, s89, 0
	global_load_ushort v230, v235, s[82:83]
	s_add_u32 s84, s88, 0x13015000
	s_addc_u32 s85, s89, 0
	global_load_ushort v231, v235, s[84:85] offset:3072
	s_add_i32 s22, 0, 0x11000
	s_nop 0
	s_add_i32 s23, s22, s30
	s_waitcnt vmcnt(31)
	v_lshlrev_b32_e32 v40, 16, v200
	v_mul_f32_e32 v11, 0x3d372713, v40
	v_mul_f32_e32 v11, v11, v40
	s_waitcnt vmcnt(30)
	v_lshlrev_b32_e32 v41, 16, v201
	v_mov_b32_e32 v12, v40
	v_fmac_f32_e32 v12, v11, v12
	v_mul_f32_e32 v11, 0x3f4c422a, v12
	v_add_f32_e32 v11, v11, v11
	v_mul_f32_e32 v11, 0x3fb8aa3b, v11
	v_exp_f32_e32 v11, v11
	v_mov_b32_e32 v13, v41
	v_add_f32_e32 v11, 1.0, v11
	v_rcp_f32_e32 v12, v11
	v_mul_f32_e32 v11, 0x3d372713, v41
	v_mul_f32_e32 v11, v11, v41
	v_fmac_f32_e32 v13, v11, v13
	v_mul_f32_e32 v11, 0x3f4c422a, v13
	v_add_f32_e32 v11, v11, v11
	v_mul_f32_e32 v11, 0x3fb8aa3b, v11
	v_exp_f32_e32 v11, v11
	v_pk_mul_f32 v[40:41], v[40:41], 0.5 op_sel_hi:[1,0]
	v_add_f32_e32 v11, 1.0, v11
	v_rcp_f32_e32 v13, v11
	s_nop 0
	v_pk_fma_f32 v[42:43], v[12:13], 2.0, 1.0 op_sel_hi:[1,0,0] neg_lo:[1,0,0] neg_hi:[1,0,0]
	s_nop 0
	v_pk_add_f32 v[42:43], v[42:43], 1.0 op_sel_hi:[1,0]
	s_nop 0
	s_nop 1
	s_waitcnt vmcnt(28)
	v_lshlrev_b32_e32 v13, 16, v203
	s_waitcnt vmcnt(29)
	v_lshlrev_b32_e32 v12, 16, v202
	v_mul_f32_e32 v11, 0x3d372713, v12
	v_mul_f32_e32 v11, v11, v12
	v_mov_b32_e32 v14, v12
	v_fmac_f32_e32 v14, v11, v14
	v_mul_f32_e32 v11, 0x3f4c422a, v14
	v_add_f32_e32 v11, v11, v11
	v_mul_f32_e32 v11, 0x3fb8aa3b, v11
	v_exp_f32_e32 v11, v11
	v_mov_b32_e32 v15, v13
	v_add_f32_e32 v11, 1.0, v11
	v_rcp_f32_e32 v14, v11
	v_mul_f32_e32 v11, 0x3d372713, v13
	v_mul_f32_e32 v11, v11, v13
	v_fmac_f32_e32 v15, v11, v15
	v_mul_f32_e32 v11, 0x3f4c422a, v15
	v_add_f32_e32 v11, v11, v11
	v_mul_f32_e32 v11, 0x3fb8aa3b, v11
	v_exp_f32_e32 v11, v11
	v_pk_mul_f32 v[12:13], v[12:13], 0.5 op_sel_hi:[1,0]
	v_add_f32_e32 v11, 1.0, v11
	v_rcp_f32_e32 v15, v11
	s_nop 0
	v_pk_fma_f32 v[14:15], v[14:15], 2.0, 1.0 op_sel_hi:[1,0,0] neg_lo:[1,0,0] neg_hi:[1,0,0]
	s_nop 0
	v_pk_add_f32 v[14:15], v[14:15], 1.0 op_sel_hi:[1,0]
	s_waitcnt vmcnt(26)
; __device__ __forceinline__ float gelu_tanh(float x) {
;     const float u = 0.7978845608028654f * (x + 0.044715f * x * x * x);
;     const float e = __expf(2.0f * u);
;     const float th = 1.0f - 2.0f * __builtin_amdgcn_rcpf(e + 1.0f);
;     return 0.5f * x * (1.0f + th);
; }
; __device__ __forceinline__ void gmlp_fast(KArgs ap, int l, LAS unsigned char* lds, const Ctx cx) {
;     ...
;                 for (int i = 0; i < 16; ++i) { const int s = wave * 16 + i; const float x = gelu_tanh(bf2f(z[(t0 + s) * DIN + ZGV + ch])); vv[i] = (x - ST[2 * s]) * ST[2 * s + 1] * gg + bb; }
	v_lshlrev_b32_e32 v17, 16, v205
	s_waitcnt vmcnt(27)
	v_lshlrev_b32_e32 v16, 16, v204
	v_mul_f32_e32 v11, 0x3d372713, v16
	v_mul_f32_e32 v11, v11, v16
	v_mov_b32_e32 v18, v16
	v_fmac_f32_e32 v18, v11, v18
	v_mul_f32_e32 v11, 0x3f4c422a, v18
	v_add_f32_e32 v11, v11, v11
	v_mul_f32_e32 v11, 0x3fb8aa3b, v11
	v_exp_f32_e32 v11, v11
	v_mov_b32_e32 v19, v17
	v_add_f32_e32 v11, 1.0, v11
	v_rcp_f32_e32 v18, v11
	v_mul_f32_e32 v11, 0x3d372713, v17
	v_mul_f32_e32 v11, v11, v17
	v_fmac_f32_e32 v19, v11, v19
	v_mul_f32_e32 v11, 0x3f4c422a, v19
	v_add_f32_e32 v11, v11, v11
	v_mul_f32_e32 v11, 0x3fb8aa3b, v11
	v_exp_f32_e32 v11, v11
	s_nop 0
	v_add_f32_e32 v11, 1.0, v11
	v_rcp_f32_e32 v19, v11
	s_nop 0
	v_pk_fma_f32 v[22:23], v[18:19], 2.0, 1.0 op_sel_hi:[1,0,0] neg_lo:[1,0,0] neg_hi:[1,0,0]
	s_nop 0
	v_pk_add_f32 v[22:23], v[22:23], 1.0 op_sel_hi:[1,0]
	s_nop 0
	s_waitcnt vmcnt(25)
	v_lshlrev_b32_e32 v20, 16, v206
	v_mul_f32_e32 v11, 0x3d372713, v20
	v_mul_f32_e32 v11, v11, v20
	s_waitcnt vmcnt(24)
	v_lshlrev_b32_e32 v21, 16, v207
	v_mov_b32_e32 v18, v20
	v_fmac_f32_e32 v18, v11, v18
	v_mul_f32_e32 v11, 0x3f4c422a, v18
	v_add_f32_e32 v11, v11, v11
	v_mul_f32_e32 v11, 0x3fb8aa3b, v11
	v_exp_f32_e32 v11, v11
	v_mov_b32_e32 v19, v21
	v_add_f32_e32 v11, 1.0, v11
	v_rcp_f32_e32 v18, v11
	v_mul_f32_e32 v11, 0x3d372713, v21
	v_mul_f32_e32 v11, v11, v21
	v_fmac_f32_e32 v19, v11, v19
	v_mul_f32_e32 v11, 0x3f4c422a, v19
	v_add_f32_e32 v11, v11, v11
	v_mul_f32_e32 v11, 0x3fb8aa3b, v11
	v_exp_f32_e32 v11, v11
	v_pk_mul_f32 v[20:21], v[20:21], 0.5 op_sel_hi:[1,0]
	v_add_f32_e32 v11, 1.0, v11
	v_rcp_f32_e32 v19, v11
	s_nop 0
	v_pk_fma_f32 v[28:29], v[18:19], 2.0, 1.0 op_sel_hi:[1,0,0] neg_lo:[1,0,0] neg_hi:[1,0,0]
	s_nop 1
	s_nop 1
	s_waitcnt vmcnt(22)
	v_lshlrev_b32_e32 v19, 16, v209
	s_waitcnt vmcnt(23)
	v_lshlrev_b32_e32 v18, 16, v208
	v_mul_f32_e32 v11, 0x3d372713, v18
	v_mul_f32_e32 v11, v11, v18
	v_mov_b32_e32 v24, v18
	v_fmac_f32_e32 v24, v11, v24
	v_mul_f32_e32 v11, 0x3f4c422a, v24
	v_add_f32_e32 v11, v11, v11
	v_mul_f32_e32 v11, 0x3fb8aa3b, v11
	v_exp_f32_e32 v11, v11
	v_mov_b32_e32 v25, v19
	v_add_f32_e32 v11, 1.0, v11
	v_rcp_f32_e32 v24, v11
	v_mul_f32_e32 v11, 0x3d372713, v19
	v_mul_f32_e32 v11, v11, v19
	v_fmac_f32_e32 v25, v11, v25
	v_mul_f32_e32 v11, 0x3f4c422a, v25
	v_add_f32_e32 v11, v11, v11
	v_mul_f32_e32 v11, 0x3fb8aa3b, v11
	v_exp_f32_e32 v11, v11
	v_pk_mul_f32 v[18:19], v[18:19], 0.5 op_sel_hi:[1,0]
	v_add_f32_e32 v11, 1.0, v11
	v_rcp_f32_e32 v25, v11
	s_nop 0
	v_pk_fma_f32 v[26:27], v[24:25], 2.0, 1.0 op_sel_hi:[1,0,0] neg_lo:[1,0,0] neg_hi:[1,0,0]
	s_nop 1
	s_nop 1
	s_waitcnt vmcnt(20)
	v_lshlrev_b32_e32 v25, 16, v211
	s_waitcnt vmcnt(21)
	v_lshlrev_b32_e32 v24, 16, v210
	v_mul_f32_e32 v11, 0x3d372713, v24
	v_mul_f32_e32 v11, v11, v24
	v_mov_b32_e32 v30, v24
	v_fmac_f32_e32 v30, v11, v30
	v_mul_f32_e32 v11, 0x3f4c422a, v30
	v_add_f32_e32 v11, v11, v11
	v_mul_f32_e32 v11, 0x3fb8aa3b, v11
	v_exp_f32_e32 v11, v11
	v_mov_b32_e32 v31, v25
	v_add_f32_e32 v11, 1.0, v11
	v_rcp_f32_e32 v30, v11
	v_mul_f32_e32 v11, 0x3d372713, v25
	v_mul_f32_e32 v11, v11, v25
	v_fmac_f32_e32 v31, v11, v31
	v_mul_f32_e32 v11, 0x3f4c422a, v31
	v_add_f32_e32 v11, v11, v11
	v_mul_f32_e32 v11, 0x3fb8aa3b, v11
	v_exp_f32_e32 v11, v11
	s_nop 0
	v_add_f32_e32 v11, 1.0, v11
	v_rcp_f32_e32 v31, v11
	s_nop 0
	v_pk_fma_f32 v[30:31], v[30:31], 2.0, 1.0 op_sel_hi:[1,0,0] neg_lo:[1,0,0] neg_hi:[1,0,0]
	s_nop 0
	s_nop 1
	s_nop 1
	s_waitcnt vmcnt(18)
	v_lshlrev_b32_e32 v33, 16, v213
	s_waitcnt vmcnt(19)
	v_lshlrev_b32_e32 v32, 16, v212
	v_mul_f32_e32 v11, 0x3d372713, v32
	v_mul_f32_e32 v11, v11, v32
	v_mov_b32_e32 v36, v32
	v_fmac_f32_e32 v36, v11, v36
	v_mul_f32_e32 v11, 0x3f4c422a, v36
	v_add_f32_e32 v11, v11, v11
	v_mul_f32_e32 v11, 0x3fb8aa3b, v11
	v_exp_f32_e32 v11, v11
	v_mov_b32_e32 v37, v33
	s_waitcnt vmcnt(17)
	v_lshlrev_b32_e32 v35, 16, v214
	v_add_f32_e32 v11, 1.0, v11
	v_rcp_f32_e32 v36, v11
	v_mul_f32_e32 v11, 0x3d372713, v33
	v_mul_f32_e32 v11, v11, v33
	v_fmac_f32_e32 v37, v11, v37
	v_mul_f32_e32 v11, 0x3f4c422a, v37
	v_add_f32_e32 v11, v11, v11
	v_mul_f32_e32 v11, 0x3fb8aa3b, v11
	v_exp_f32_e32 v11, v11
	s_nop 0
	v_add_f32_e32 v11, 1.0, v11
	v_rcp_f32_e32 v37, v11
	v_mov_b32_e32 v39, v35
	v_pk_fma_f32 v[36:37], v[36:37], 2.0, 1.0 op_sel_hi:[1,0,0] neg_lo:[1,0,0] neg_hi:[1,0,0]
	s_waitcnt vmcnt(16)
	v_lshlrev_b32_e32 v34, 16, v215
	v_mul_f32_e32 v11, 0x3d372713, v34
	v_mul_f32_e32 v11, v11, v34
	v_mov_b32_e32 v38, v34
	v_fmac_f32_e32 v38, v11, v38
	v_mul_f32_e32 v11, 0x3f4c422a, v38
	v_add_f32_e32 v11, v11, v11
	v_mul_f32_e32 v11, 0x3fb8aa3b, v11
	v_exp_f32_e32 v11, v11
	s_nop 0
	v_add_f32_e32 v11, 1.0, v11
	v_rcp_f32_e32 v38, v11
	v_mul_f32_e32 v11, 0x3d372713, v35
	v_mul_f32_e32 v11, v11, v35
	v_fmac_f32_e32 v39, v11, v39
	v_mul_f32_e32 v11, 0x3f4c422a, v39
	v_add_f32_e32 v11, v11, v11
	v_mul_f32_e32 v11, 0x3fb8aa3b, v11
	v_exp_f32_e32 v11, v11
	s_nop 0
	v_add_f32_e32 v11, 1.0, v11
	v_rcp_f32_e32 v39, v11
	v_mov_b32_e32 v11, s23
	ds_read_b128 v[44:47], v11
	ds_read_b128 v[48:51], v11 offset:16
	s_add_i32 s23, s22, s31
	v_pk_fma_f32 v[38:39], v[38:39], 2.0, 1.0 op_sel_hi:[1,0,0] neg_lo:[1,0,0] neg_hi:[1,0,0]
	s_waitcnt lgkmcnt(1)
	v_mov_b32_e32 v52, v44
	s_waitcnt lgkmcnt(0)
	v_mov_b32_e32 v53, v48
	v_pk_fma_f32 v[40:41], v[40:41], v[42:43], v[52:53] neg_lo:[0,0,1] neg_hi:[0,0,1]
	v_mov_b32_e32 v48, v45
	v_pk_mul_f32 v[40:41], v[48:49], v[40:41]
	v_pk_mul_f32 v[48:49], v[16:17], 0.5 op_sel_hi:[1,0]
	v_pk_fma_f32 v[44:45], v[8:9], v[40:41], v[10:11] op_sel_hi:[0,1,0]
	v_mov_b32_e32 v40, v46
	v_mov_b32_e32 v41, v50
	v_pk_fma_f32 v[12:13], v[12:13], v[14:15], v[40:41] neg_lo:[0,0,1] neg_hi:[0,0,1]
	v_mov_b32_e32 v50, v47
	v_pk_mul_f32 v[12:13], v[50:51], v[12:13]
	s_nop 0
	v_pk_fma_f32 v[46:47], v[8:9], v[12:13], v[10:11] op_sel_hi:[0,1,0]
	v_mov_b32_e32 v12, s23
	ds_read_b128 v[14:17], v12
	ds_read_b128 v[40:43], v12 offset:16
	s_add_i32 s23, s22, s38
	s_add_i32 s22, s22, s39
	s_waitcnt lgkmcnt(1)
; #define LAS __attribute__((address_space(3)))
; __device__ __forceinline__ unsigned pk2(float lo, float hi) { return f2bf(lo) | (f2bf(hi) << 16); }
; __device__ __forceinline__ void gmlp_fast(KArgs ap, int l, LAS unsigned char* lds, const Ctx cx) {
;     ...
;                 for (int i = 0; i < 16; ++i) { const int s = wave * 16 + i; const float x = gelu_tanh(bf2f(z[(t0 + s) * DIN + ZGV + ch])); vv[i] = (x - ST[2 * s]) * ST[2 * s + 1] * gg + bb; }
;                 u32x4 w0, w1;
;                 w0.x = pk2(vv[0], vv[1]); w0.y = pk2(vv[2], vv[3]); w0.z = pk2(vv[4], vv[5]); w0.w = pk2(vv[6], vv[7]);
;                 w1.x = pk2(vv[8], vv[9]); w1.y = pk2(vv[10], vv[11]); w1.z = pk2(vv[12], vv[13]); w1.w = pk2(vv[14], vv[15]);
;                 *(LAS u32x4*)(VT + chl * 272 + wave * 32) = w0; *(LAS u32x4*)(VT + chl * 272 + wave * 32 + 16) = w1; }
	v_mov_b32_e32 v50, v14
	s_waitcnt lgkmcnt(0)
	v_mov_b32_e32 v51, v40
	v_pk_fma_f32 v[22:23], v[48:49], v[22:23], v[50:51] neg_lo:[0,0,1] neg_hi:[0,0,1]
	v_mov_b32_e32 v40, v15
	v_pk_mul_f32 v[14:15], v[40:41], v[22:23]
	v_pk_add_f32 v[22:23], v[28:29], 1.0 op_sel_hi:[1,0]
	v_mov_b32_e32 v28, v16
	v_mov_b32_e32 v29, v42
	v_pk_fma_f32 v[20:21], v[20:21], v[22:23], v[28:29] neg_lo:[0,0,1] neg_hi:[0,0,1]
	v_mov_b32_e32 v42, v17
	v_pk_mul_f32 v[16:17], v[42:43], v[20:21]
	v_pk_fma_f32 v[14:15], v[8:9], v[14:15], v[10:11] op_sel_hi:[0,1,0]
	v_pk_fma_f32 v[16:17], v[8:9], v[16:17], v[10:11] op_sel_hi:[0,1,0]
	s_nop 0
	v_cvt_pk_bf16_f32 v22, v14, v16
	v_cvt_pk_bf16_f32 v23, v15, v17
	v_mov_b32_e32 v13, s23
	v_cvt_pk_bf16_f32 v21, v45, v47
	v_cvt_pk_bf16_f32 v20, v44, v46
	v_pk_add_f32 v[40:41], v[26:27], 1.0 op_sel_hi:[1,0]
	ds_read_b128 v[14:17], v13
	ds_read_b128 v[26:29], v13 offset:16
	s_waitcnt lgkmcnt(1)
	v_mov_b32_e32 v42, v14
	s_waitcnt lgkmcnt(0)
	v_mov_b32_e32 v43, v26
	v_pk_fma_f32 v[18:19], v[18:19], v[40:41], v[42:43] neg_lo:[0,0,1] neg_hi:[0,0,1]
	v_mov_b32_e32 v26, v15
	v_pk_mul_f32 v[14:15], v[26:27], v[18:19]
	v_pk_add_f32 v[18:19], v[30:31], 1.0 op_sel_hi:[1,0]
	v_pk_fma_f32 v[40:41], v[8:9], v[14:15], v[10:11] op_sel_hi:[0,1,0]
	v_pk_mul_f32 v[14:15], v[24:25], 0.5 op_sel_hi:[1,0]
	v_mov_b32_e32 v24, v16
	v_mov_b32_e32 v25, v28
	v_pk_fma_f32 v[14:15], v[14:15], v[18:19], v[24:25] neg_lo:[0,0,1] neg_hi:[0,0,1]
	v_mov_b32_e32 v28, v17
	v_pk_mul_f32 v[14:15], v[28:29], v[14:15]
	v_pk_mul_f32 v[30:31], v[32:33], 0.5 op_sel_hi:[1,0]
	v_pk_fma_f32 v[28:29], v[8:9], v[14:15], v[10:11] op_sel_hi:[0,1,0]
	v_mov_b32_e32 v14, s22
	ds_read_b128 v[16:19], v14
	ds_read_b128 v[24:27], v14 offset:16
	v_pk_add_f32 v[32:33], v[36:37], 1.0 op_sel_hi:[1,0]
	v_bfe_u32 v15, v29, 16, 1
	v_add3_u32 v15, v29, v15, s45
	s_waitcnt lgkmcnt(1)
	v_mov_b32_e32 v36, v16
	s_waitcnt lgkmcnt(0)
	v_mov_b32_e32 v37, v24
	v_pk_fma_f32 v[30:31], v[30:31], v[32:33], v[36:37] neg_lo:[0,0,1] neg_hi:[0,0,1]
	v_mov_b32_e32 v24, v17
	v_pk_mul_f32 v[16:17], v[24:25], v[30:31]
	v_pk_mul_f32 v[24:25], v[34:35], 0.5 op_sel_hi:[1,0]
	v_pk_add_f32 v[30:31], v[38:39], 1.0 op_sel_hi:[1,0]
	v_mov_b32_e32 v32, v18
	v_mov_b32_e32 v33, v26
	v_pk_fma_f32 v[24:25], v[24:25], v[30:31], v[32:33] neg_lo:[0,0,1] neg_hi:[0,0,1]
	v_mov_b32_e32 v26, v19
	v_pk_mul_f32 v[18:19], v[26:27], v[24:25]
	v_pk_fma_f32 v[16:17], v[8:9], v[16:17], v[10:11] op_sel_hi:[0,1,0]
	v_pk_fma_f32 v[18:19], v[8:9], v[18:19], v[10:11] op_sel_hi:[0,1,0]
	s_nop 0
	v_bfe_u32 v8, v19, 16, 1
	v_bfe_u32 v10, v18, 16, 1
	v_add3_u32 v10, v18, v10, s45
	v_add3_u32 v8, v19, v8, s45
	v_bfe_u32 v19, v41, 16, 1
	v_bfe_u32 v25, v16, 16, 1
	v_bfe_u32 v26, v17, 16, 1
	v_add3_u32 v17, v17, v26, s45
	v_add3_u32 v16, v16, v25, s45
	v_add3_u32 v19, v41, v19, s45
	v_lshrrev_b32_e32 v26, 16, v19
	v_lshrrev_b32_e32 v16, 16, v16
	v_lshrrev_b32_e32 v17, 16, v17
	v_and_or_b32 v19, v8, s43, v17
	v_and_or_b32 v18, v10, s43, v16
	v_and_or_b32 v17, v15, s43, v26
	v_cvt_pk_bf16_f32 v16, v40, v28
	ds_write_b128 v9, v[20:23]
	ds_write_b128 v9, v[16:19] offset:16
	s_mov_b32 s22, 0x13001000
	s_mov_b32 s22, 0x13003000
	s_nop 0
	v_mov_b32_e32 v8, v232
	v_mov_b32_e32 v10, v233
	s_add_u32 s20, s20, 0x100
	s_nop 0
	s_addc_u32 s21, s21, 0
	s_nop 0
	v_lshl_add_u64 v[2:3], v[2:3], 0, s[36:37]
	v_lshl_add_u64 v[4:5], v[4:5], 0, s[36:37]
	s_cmpk_eq_i32 s20, 0x200
	s_waitcnt vmcnt(0)
	v_lshlrev_b32_e32 v19, 16, v217
	v_lshlrev_b32_e32 v18, 16, v216
	v_mul_f32_e32 v15, 0x3d372713, v18
	v_mul_f32_e32 v15, v15, v18
	v_mov_b32_e32 v20, v18
	v_fmac_f32_e32 v20, v15, v20
	v_mul_f32_e32 v15, 0x3f4c422a, v20
	v_add_f32_e32 v15, v15, v15
	v_mul_f32_e32 v15, 0x3fb8aa3b, v15
	v_exp_f32_e32 v15, v15
	v_mov_b32_e32 v21, v19
	v_pk_mul_f32 v[52:53], v[18:19], 0.5 op_sel_hi:[1,0]
	v_add_f32_e32 v15, 1.0, v15
	v_rcp_f32_e32 v20, v15
	v_mul_f32_e32 v15, 0x3d372713, v19
	v_mul_f32_e32 v15, v15, v19
	v_fmac_f32_e32 v21, v15, v21
	v_mul_f32_e32 v15, 0x3f4c422a, v21
	v_add_f32_e32 v15, v15, v15
	v_mul_f32_e32 v15, 0x3fb8aa3b, v15
	v_exp_f32_e32 v15, v15
	s_nop 0
	v_add_f32_e32 v15, 1.0, v15
	v_rcp_f32_e32 v21, v15
	s_nop 0
	v_pk_fma_f32 v[20:21], v[20:21], 2.0, 1.0 op_sel_hi:[1,0,0] neg_lo:[1,0,0] neg_hi:[1,0,0]
	s_nop 0
	v_pk_add_f32 v[54:55], v[20:21], 1.0 op_sel_hi:[1,0]
	v_lshlrev_b32_e32 v24, 16, v218
	v_mul_f32_e32 v15, 0x3d372713, v24
	v_mul_f32_e32 v15, v15, v24
	v_lshlrev_b32_e32 v25, 16, v219
	v_mov_b32_e32 v22, v24
	v_fmac_f32_e32 v22, v15, v22
	v_mul_f32_e32 v15, 0x3f4c422a, v22
	v_add_f32_e32 v15, v15, v15
	v_mul_f32_e32 v15, 0x3fb8aa3b, v15
	v_exp_f32_e32 v15, v15
	v_mov_b32_e32 v23, v25
	v_add_f32_e32 v15, 1.0, v15
	v_rcp_f32_e32 v22, v15
	v_mul_f32_e32 v15, 0x3d372713, v25
	v_mul_f32_e32 v15, v15, v25
	v_fmac_f32_e32 v23, v15, v23
	v_mul_f32_e32 v15, 0x3f4c422a, v23
	v_add_f32_e32 v15, v15, v15
	v_mul_f32_e32 v15, 0x3fb8aa3b, v15
	v_exp_f32_e32 v15, v15
	s_nop 0
	v_add_f32_e32 v15, 1.0, v15
	v_rcp_f32_e32 v23, v15
	s_nop 0
	v_pk_fma_f32 v[26:27], v[22:23], 2.0, 1.0 op_sel_hi:[1,0,0] neg_lo:[1,0,0] neg_hi:[1,0,0]
	s_nop 1
	v_lshlrev_b32_e32 v28, 16, v220
	v_mul_f32_e32 v15, 0x3d372713, v28
	v_mul_f32_e32 v15, v15, v28
	v_lshlrev_b32_e32 v29, 16, v221
	v_mov_b32_e32 v22, v28
	v_fmac_f32_e32 v22, v15, v22
	v_mul_f32_e32 v15, 0x3f4c422a, v22
	v_add_f32_e32 v15, v15, v15
	v_mul_f32_e32 v15, 0x3fb8aa3b, v15
	v_exp_f32_e32 v15, v15
	v_mov_b32_e32 v23, v29
	v_add_f32_e32 v15, 1.0, v15
	v_rcp_f32_e32 v22, v15
	v_mul_f32_e32 v15, 0x3d372713, v29
	v_mul_f32_e32 v15, v15, v29
	v_fmac_f32_e32 v23, v15, v23
	v_mul_f32_e32 v15, 0x3f4c422a, v23
	v_add_f32_e32 v15, v15, v15
; #define LAS __attribute__((address_space(3)))
; __device__ __forceinline__ unsigned pk2(float lo, float hi) { return f2bf(lo) | (f2bf(hi) << 16); }
; __device__ __forceinline__ float gelu_tanh(float x) {
;     const float u = 0.7978845608028654f * (x + 0.044715f * x * x * x);
;     const float e = __expf(2.0f * u);
;     const float th = 1.0f - 2.0f * __builtin_amdgcn_rcpf(e + 1.0f);
;     return 0.5f * x * (1.0f + th);
; }
; __device__ __forceinline__ void gmlp_fast(KArgs ap, int l, LAS unsigned char* lds, const Ctx cx) {
;     ...
;                 for (int i = 0; i < 16; ++i) { const int s = wave * 16 + i; const float x = gelu_tanh(bf2f(z[(t0 + s) * DIN + ZGV + ch])); vv[i] = (x - ST[2 * s]) * ST[2 * s + 1] * gg + bb; }
;                 u32x4 w0, w1;
;                 w0.x = pk2(vv[0], vv[1]); w0.y = pk2(vv[2], vv[3]); w0.z = pk2(vv[4], vv[5]); w0.w = pk2(vv[6], vv[7]);
;                 w1.x = pk2(vv[8], vv[9]); w1.y = pk2(vv[10], vv[11]); w1.z = pk2(vv[12], vv[13]); w1.w = pk2(vv[14], vv[15]);
;                 *(LAS u32x4*)(VT + chl * 272 + wave * 32) = w0; *(LAS u32x4*)(VT + chl * 272 + wave * 32 + 16) = w1; }
	v_mul_f32_e32 v15, 0x3fb8aa3b, v15
	v_exp_f32_e32 v15, v15
	s_nop 0
	v_add_f32_e32 v15, 1.0, v15
	v_rcp_f32_e32 v23, v15
	s_nop 0
	v_pk_fma_f32 v[30:31], v[22:23], 2.0, 1.0 op_sel_hi:[1,0,0] neg_lo:[1,0,0] neg_hi:[1,0,0]
	s_nop 1
	v_lshlrev_b32_e32 v32, 16, v222
	v_mul_f32_e32 v15, 0x3d372713, v32
	v_mul_f32_e32 v15, v15, v32
	v_lshlrev_b32_e32 v33, 16, v223
	v_mov_b32_e32 v22, v32
	v_fmac_f32_e32 v22, v15, v22
	v_mul_f32_e32 v15, 0x3f4c422a, v22
	v_add_f32_e32 v15, v15, v15
	v_mul_f32_e32 v15, 0x3fb8aa3b, v15
	v_exp_f32_e32 v15, v15
	v_mov_b32_e32 v23, v33
	v_add_f32_e32 v15, 1.0, v15
	v_rcp_f32_e32 v22, v15
	v_mul_f32_e32 v15, 0x3d372713, v33
	v_mul_f32_e32 v15, v15, v33
	v_fmac_f32_e32 v23, v15, v23
	v_mul_f32_e32 v15, 0x3f4c422a, v23
	v_add_f32_e32 v15, v15, v15
	v_mul_f32_e32 v15, 0x3fb8aa3b, v15
	v_exp_f32_e32 v15, v15
	s_nop 0
	v_add_f32_e32 v15, 1.0, v15
	v_rcp_f32_e32 v23, v15
	s_nop 0
	v_pk_fma_f32 v[34:35], v[22:23], 2.0, 1.0 op_sel_hi:[1,0,0] neg_lo:[1,0,0] neg_hi:[1,0,0]
	s_nop 1
	v_lshlrev_b32_e32 v36, 16, v224
	v_mul_f32_e32 v15, 0x3d372713, v36
	v_mul_f32_e32 v15, v15, v36
	v_lshlrev_b32_e32 v37, 16, v225
	v_mov_b32_e32 v22, v36
	v_fmac_f32_e32 v22, v15, v22
	v_mul_f32_e32 v15, 0x3f4c422a, v22
	v_add_f32_e32 v15, v15, v15
	v_mul_f32_e32 v15, 0x3fb8aa3b, v15
	v_exp_f32_e32 v15, v15
	v_mov_b32_e32 v23, v37
	v_add_f32_e32 v15, 1.0, v15
	v_rcp_f32_e32 v22, v15
	v_mul_f32_e32 v15, 0x3d372713, v37
	v_mul_f32_e32 v15, v15, v37
	v_fmac_f32_e32 v23, v15, v23
	v_mul_f32_e32 v15, 0x3f4c422a, v23
	v_add_f32_e32 v15, v15, v15
	v_mul_f32_e32 v15, 0x3fb8aa3b, v15
	v_exp_f32_e32 v15, v15
	s_nop 0
	v_add_f32_e32 v15, 1.0, v15
	v_rcp_f32_e32 v23, v15
	s_nop 0
	v_pk_fma_f32 v[38:39], v[22:23], 2.0, 1.0 op_sel_hi:[1,0,0] neg_lo:[1,0,0] neg_hi:[1,0,0]
	s_nop 1
	v_lshlrev_b32_e32 v40, 16, v226
	v_mul_f32_e32 v15, 0x3d372713, v40
	v_mul_f32_e32 v15, v15, v40
	v_lshlrev_b32_e32 v41, 16, v227
	v_mov_b32_e32 v22, v40
	v_fmac_f32_e32 v22, v15, v22
	v_mul_f32_e32 v15, 0x3f4c422a, v22
	v_add_f32_e32 v15, v15, v15
	v_mul_f32_e32 v15, 0x3fb8aa3b, v15
	v_exp_f32_e32 v15, v15
	v_mov_b32_e32 v23, v41
	v_add_f32_e32 v15, 1.0, v15
	v_rcp_f32_e32 v22, v15
	v_mul_f32_e32 v15, 0x3d372713, v41
	v_mul_f32_e32 v15, v15, v41
	v_fmac_f32_e32 v23, v15, v23
	v_mul_f32_e32 v15, 0x3f4c422a, v23
	v_add_f32_e32 v15, v15, v15
	v_mul_f32_e32 v15, 0x3fb8aa3b, v15
	v_exp_f32_e32 v15, v15
	s_nop 0
	v_add_f32_e32 v15, 1.0, v15
	v_rcp_f32_e32 v23, v15
	s_nop 0
	v_pk_fma_f32 v[42:43], v[22:23], 2.0, 1.0 op_sel_hi:[1,0,0] neg_lo:[1,0,0] neg_hi:[1,0,0]
	s_nop 1
	v_lshlrev_b32_e32 v44, 16, v228
	v_mul_f32_e32 v15, 0x3d372713, v44
	v_mul_f32_e32 v15, v15, v44
	v_lshlrev_b32_e32 v45, 16, v229
	v_mov_b32_e32 v22, v44
	v_fmac_f32_e32 v22, v15, v22
	v_mul_f32_e32 v15, 0x3f4c422a, v22
	v_add_f32_e32 v15, v15, v15
	v_mul_f32_e32 v15, 0x3fb8aa3b, v15
	v_exp_f32_e32 v15, v15
	v_mov_b32_e32 v23, v45
	v_add_f32_e32 v15, 1.0, v15
	v_rcp_f32_e32 v22, v15
	v_mul_f32_e32 v15, 0x3d372713, v45
	v_mul_f32_e32 v15, v15, v45
	v_fmac_f32_e32 v23, v15, v23
	v_mul_f32_e32 v15, 0x3f4c422a, v23
	v_add_f32_e32 v15, v15, v15
	v_mul_f32_e32 v15, 0x3fb8aa3b, v15
	v_exp_f32_e32 v15, v15
	s_nop 0
	v_add_f32_e32 v15, 1.0, v15
	v_rcp_f32_e32 v23, v15
	s_nop 0
	v_pk_fma_f32 v[46:47], v[22:23], 2.0, 1.0 op_sel_hi:[1,0,0] neg_lo:[1,0,0] neg_hi:[1,0,0]
	s_nop 1
	s_nop 1
	v_lshlrev_b32_e32 v48, 16, v230
	v_mul_f32_e32 v15, 0x3d372713, v48
	v_mul_f32_e32 v15, v15, v48
	v_lshlrev_b32_e32 v49, 16, v231
	v_mov_b32_e32 v16, v48
	v_fmac_f32_e32 v16, v15, v16
	v_mul_f32_e32 v15, 0x3f4c422a, v16
	v_add_f32_e32 v15, v15, v15
	v_mul_f32_e32 v15, 0x3fb8aa3b, v15
	v_exp_f32_e32 v15, v15
	v_mov_b32_e32 v17, v49
	v_add_f32_e32 v15, 1.0, v15
	v_rcp_f32_e32 v16, v15
	v_mul_f32_e32 v15, 0x3d372713, v49
	v_mul_f32_e32 v15, v15, v49
	v_fmac_f32_e32 v17, v15, v17
	v_mul_f32_e32 v15, 0x3f4c422a, v17
	v_add_f32_e32 v15, v15, v15
	v_mul_f32_e32 v15, 0x3fb8aa3b, v15
	v_exp_f32_e32 v15, v15
	s_nop 0
	v_add_f32_e32 v15, 1.0, v15
	v_rcp_f32_e32 v17, v15
	s_nop 0
	v_pk_fma_f32 v[50:51], v[16:17], 2.0, 1.0 op_sel_hi:[1,0,0] neg_lo:[1,0,0] neg_hi:[1,0,0]
	ds_read_b128 v[16:19], v11
	ds_read_b128 v[20:23], v11 offset:16
	s_waitcnt lgkmcnt(1)
	v_mov_b32_e32 v56, v16
	s_waitcnt lgkmcnt(0)
	v_mov_b32_e32 v57, v20
	v_pk_fma_f32 v[52:53], v[52:53], v[54:55], v[56:57] neg_lo:[0,0,1] neg_hi:[0,0,1]
	v_mov_b32_e32 v20, v17
	v_pk_mul_f32 v[16:17], v[20:21], v[52:53]
	v_pk_add_f32 v[20:21], v[26:27], 1.0 op_sel_hi:[1,0]
	v_pk_fma_f32 v[52:53], v[8:9], v[16:17], v[10:11] op_sel_hi:[0,1,0]
	v_pk_mul_f32 v[16:17], v[24:25], 0.5 op_sel_hi:[1,0]
	v_mov_b32_e32 v24, v18
	v_mov_b32_e32 v25, v22
	v_pk_fma_f32 v[16:17], v[16:17], v[20:21], v[24:25] neg_lo:[0,0,1] neg_hi:[0,0,1]
	v_mov_b32_e32 v22, v19
	v_pk_mul_f32 v[16:17], v[22:23], v[16:17]
	v_pk_mul_f32 v[26:27], v[28:29], 0.5 op_sel_hi:[1,0]
	v_pk_fma_f32 v[24:25], v[8:9], v[16:17], v[10:11] op_sel_hi:[0,1,0]
	ds_read_b128 v[16:19], v12
	ds_read_b128 v[20:23], v12 offset:16
	v_pk_add_f32 v[28:29], v[30:31], 1.0 op_sel_hi:[1,0]
	s_waitcnt lgkmcnt(1)
	v_mov_b32_e32 v30, v16
	s_waitcnt lgkmcnt(0)
; #define LAS __attribute__((address_space(3)))
; __device__ __forceinline__ unsigned pk2(float lo, float hi) { return f2bf(lo) | (f2bf(hi) << 16); }
; __device__ __forceinline__ void gmlp_fast(KArgs ap, int l, LAS unsigned char* lds, const Ctx cx) {
;     ...
;                 for (int i = 0; i < 16; ++i) { const int s = wave * 16 + i; const float x = gelu_tanh(bf2f(z[(t0 + s) * DIN + ZGV + ch])); vv[i] = (x - ST[2 * s]) * ST[2 * s + 1] * gg + bb; }
;                 u32x4 w0, w1;
;                 w0.x = pk2(vv[0], vv[1]); w0.y = pk2(vv[2], vv[3]); w0.z = pk2(vv[4], vv[5]); w0.w = pk2(vv[6], vv[7]);
;                 w1.x = pk2(vv[8], vv[9]); w1.y = pk2(vv[10], vv[11]); w1.z = pk2(vv[12], vv[13]); w1.w = pk2(vv[14], vv[15]);
;                 *(LAS u32x4*)(VT + chl * 272 + wave * 32) = w0; *(LAS u32x4*)(VT + chl * 272 + wave * 32 + 16) = w1; }
;             __syncthreads();
;             const int gl = wave >> 2, tb = wave & 3, g = 2 * k + gl;
;             f32x16 acc[4];
; #pragma unroll
;             for (int ht = 0; ht < 4; ++ht)
; #pragma unroll
;                 for (int i = 0; i < 16; ++i) acc[ht][i] = 0.f;
;             const int tl = 32 * tb + r;
;             const float* wrow = wsp + ((size_t)g * 128 + tl) * 128 + 8 * hh;
;             f32x4 wn0 = *(const f32x4*)wrow, wn1 = *(const f32x4*)(wrow + 4);
	v_mov_b32_e32 v31, v20
	v_pk_fma_f32 v[26:27], v[26:27], v[28:29], v[30:31] neg_lo:[0,0,1] neg_hi:[0,0,1]
	v_mov_b32_e32 v20, v17
	v_pk_mul_f32 v[16:17], v[20:21], v[26:27]
	v_pk_mul_f32 v[20:21], v[32:33], 0.5 op_sel_hi:[1,0]
	v_pk_add_f32 v[26:27], v[34:35], 1.0 op_sel_hi:[1,0]
	v_mov_b32_e32 v28, v18
	v_mov_b32_e32 v29, v22
	v_pk_fma_f32 v[20:21], v[20:21], v[26:27], v[28:29] neg_lo:[0,0,1] neg_hi:[0,0,1]
	v_mov_b32_e32 v22, v19
	v_pk_mul_f32 v[18:19], v[22:23], v[20:21]
	v_pk_fma_f32 v[16:17], v[8:9], v[16:17], v[10:11] op_sel_hi:[0,1,0]
	v_pk_fma_f32 v[18:19], v[8:9], v[18:19], v[10:11] op_sel_hi:[0,1,0]
	s_nop 0
	v_bfe_u32 v11, v19, 16, 1
	v_bfe_u32 v12, v18, 16, 1
	v_add3_u32 v12, v18, v12, s45
	v_add3_u32 v11, v19, v11, s45
	v_bfe_u32 v21, v16, 16, 1
	v_bfe_u32 v22, v17, 16, 1
	v_add3_u32 v17, v17, v22, s45
	v_add3_u32 v16, v16, v21, s45
	v_lshrrev_b32_e32 v16, 16, v16
	v_lshrrev_b32_e32 v17, 16, v17
	v_and_or_b32 v19, v11, s43, v17
	v_and_or_b32 v18, v12, s43, v16
	v_cvt_pk_bf16_f32 v17, v53, v25
	v_cvt_pk_bf16_f32 v16, v52, v24
	ds_read_b128 v[20:23], v13
	ds_read_b128 v[24:27], v13 offset:16
	v_pk_mul_f32 v[28:29], v[36:37], 0.5 op_sel_hi:[1,0]
	v_pk_add_f32 v[30:31], v[38:39], 1.0 op_sel_hi:[1,0]
	s_waitcnt lgkmcnt(1)
	v_mov_b32_e32 v12, v20
	s_waitcnt lgkmcnt(0)
	v_mov_b32_e32 v13, v24
	v_pk_fma_f32 v[12:13], v[28:29], v[30:31], v[12:13] neg_lo:[0,0,1] neg_hi:[0,0,1]
	v_mov_b32_e32 v24, v21
	v_pk_mul_f32 v[12:13], v[24:25], v[12:13]
	v_pk_add_f32 v[20:21], v[42:43], 1.0 op_sel_hi:[1,0]
	v_pk_fma_f32 v[24:25], v[8:9], v[12:13], v[10:11] op_sel_hi:[0,1,0]
	v_pk_mul_f32 v[12:13], v[40:41], 0.5 op_sel_hi:[1,0]
	v_mov_b32_e32 v28, v22
	v_mov_b32_e32 v29, v26
	v_pk_fma_f32 v[12:13], v[12:13], v[20:21], v[28:29] neg_lo:[0,0,1] neg_hi:[0,0,1]
	v_mov_b32_e32 v26, v23
	v_pk_mul_f32 v[12:13], v[26:27], v[12:13]
	v_pk_mul_f32 v[28:29], v[44:45], 0.5 op_sel_hi:[1,0]
	v_pk_fma_f32 v[26:27], v[8:9], v[12:13], v[10:11] op_sel_hi:[0,1,0]
	ds_read_b128 v[20:23], v14
	ds_read_b128 v[12:15], v14 offset:16
	v_pk_add_f32 v[30:31], v[46:47], 1.0 op_sel_hi:[1,0]
	s_waitcnt lgkmcnt(1)
	v_mov_b32_e32 v32, v20
	s_waitcnt lgkmcnt(0)
	v_mov_b32_e32 v33, v12
	v_pk_fma_f32 v[28:29], v[28:29], v[30:31], v[32:33] neg_lo:[0,0,1] neg_hi:[0,0,1]
	v_mov_b32_e32 v12, v21
	v_pk_mul_f32 v[12:13], v[12:13], v[28:29]
	v_pk_mul_f32 v[20:21], v[48:49], 0.5 op_sel_hi:[1,0]
	v_pk_add_f32 v[28:29], v[50:51], 1.0 op_sel_hi:[1,0]
	v_mov_b32_e32 v30, v22
	v_mov_b32_e32 v31, v14
	v_pk_fma_f32 v[20:21], v[20:21], v[28:29], v[30:31] neg_lo:[0,0,1] neg_hi:[0,0,1]
	v_mov_b32_e32 v14, v23
	v_pk_mul_f32 v[14:15], v[14:15], v[20:21]
	v_pk_fma_f32 v[12:13], v[8:9], v[12:13], v[10:11] op_sel_hi:[0,1,0]
	v_pk_fma_f32 v[10:11], v[8:9], v[14:15], v[10:11] op_sel_hi:[0,1,0]
	s_nop 0
	v_cvt_pk_bf16_f32 v12, v12, v10
	v_cvt_pk_bf16_f32 v13, v13, v11
	v_cvt_pk_bf16_f32 v11, v25, v27
	v_cvt_pk_bf16_f32 v10, v24, v26
	ds_write_b128 v9, v[16:19] offset:17408
	ds_write_b128 v9, v[10:13] offset:17424
	v_add_u32_e32 v9, 0x8800, v9
	s_cbranch_scc0 .LBB0_162
	s_lshl_b32 s13, s13, 1
	s_add_i32 s20, s13, s28
	s_ashr_i32 s21, s20, 31
	s_lshl_b64 s[22:23], s[20:21], 16
	v_lshl_add_u64 v[0:1], v[82:83], 0, s[22:23]
	s_waitcnt lgkmcnt(0)
	s_barrier
	global_load_dwordx4 v[72:75], v[0:1], off offset:16
	global_load_dwordx4 v[76:79], v[0:1], off
	v_mov_b32_e32 v0, 0
	v_lshl_add_u64 v[98:99], v[90:91], 0, s[22:23]
	s_mov_b32 s13, 0
	v_mov_b32_e32 v93, v107
	s_mov_b32 s21, 0
	v_mov_b32_e32 v1, v0
	v_mov_b32_e32 v2, v0
	v_mov_b32_e32 v3, v0
	v_mov_b32_e32 v4, v0
	v_mov_b32_e32 v5, v0
	v_mov_b32_e32 v6, v0
	v_mov_b32_e32 v7, v0
	v_mov_b32_e32 v8, v0
	v_mov_b32_e32 v9, v0
	v_mov_b32_e32 v10, v0
	v_mov_b32_e32 v11, v0
	v_mov_b32_e32 v12, v0
	v_mov_b32_e32 v13, v0
	v_mov_b32_e32 v14, v0
	v_mov_b32_e32 v15, v0
	v_mov_b32_e32 v16, v0
	v_mov_b32_e32 v17, v0
	v_mov_b32_e32 v18, v0
	v_mov_b32_e32 v19, v0
	v_mov_b32_e32 v20, v0
	v_mov_b32_e32 v21, v0
	v_mov_b32_e32 v22, v0
	v_mov_b32_e32 v23, v0
	v_mov_b32_e32 v24, v0
	v_mov_b32_e32 v25, v0
	v_mov_b32_e32 v26, v0
	v_mov_b32_e32 v27, v0
	v_mov_b32_e32 v28, v0
	v_mov_b32_e32 v29, v0
	v_mov_b32_e32 v30, v0
	v_mov_b32_e32 v31, v0
	v_mov_b32_e32 v32, v0
	v_mov_b32_e32 v33, v0
	v_mov_b32_e32 v34, v0
	v_mov_b32_e32 v35, v0
	v_mov_b32_e32 v36, v0
	v_mov_b32_e32 v37, v0
	v_mov_b32_e32 v38, v0
	v_mov_b32_e32 v39, v0
	v_mov_b32_e32 v40, v0
	v_mov_b32_e32 v41, v0
	v_mov_b32_e32 v42, v0
	v_mov_b32_e32 v43, v0
	v_mov_b32_e32 v44, v0
	v_mov_b32_e32 v45, v0
	v_mov_b32_e32 v46, v0
	v_mov_b32_e32 v47, v0
	v_mov_b32_e32 v48, v0
	v_mov_b32_e32 v49, v0
	v_mov_b32_e32 v50, v0
	v_mov_b32_e32 v51, v0
	v_mov_b32_e32 v52, v0
	v_mov_b32_e32 v53, v0
	v_mov_b32_e32 v54, v0
	v_mov_b32_e32 v55, v0
	v_mov_b32_e32 v56, v0
	v_mov_b32_e32 v57, v0
	v_mov_b32_e32 v58, v0
	v_mov_b32_e32 v59, v0
	v_mov_b32_e32 v60, v0
	v_mov_b32_e32 v61, v0
	v_mov_b32_e32 v62, v0
	v_mov_b32_e32 v63, v0
	s_waitcnt vmcnt(1)
	v_mov_b64_e32 v[68:69], v[72:73]
	s_waitcnt vmcnt(0)
	v_mov_b64_e32 v[64:65], v[76:77]
	v_mov_b64_e32 v[66:67], v[78:79]
	v_mov_b64_e32 v[70:71], v[74:75]
	s_branch .LBB0_165

; __device__ __forceinline__ unsigned pk2(float lo, float hi) { return f2bf(lo) | (f2bf(hi) << 16); }
; __device__ __forceinline__ void phase_branch_norm(bf16_t* y, const float* ga, const float* gs, const float* gg, const Ctx cx) {
;     ...
;     for (int m = gw; m < T; m += NGW) {
;         bf16_t* yr = y + (size_t)m * DM + lane * 8;
;         float v[4][8]; float ss[4];
; #pragma unroll
;         for (int j = 0; j < 4; ++j) { const u32x4 w = *(const u32x4*)(yr + j * 512);
;             v[j][0] = bflo(w.x); v[j][1] = bfhi(w.x); v[j][2] = bflo(w.y); v[j][3] = bfhi(w.y); v[j][4] = bflo(w.z); v[j][5] = bfhi(w.z); v[j][6] = bflo(w.w); v[j][7] = bfhi(w.w);
;             float s = 0.f;
; #pragma unroll
;             for (int e = 0; e < 8; ++e) s += v[j][e] * v[j][e];
;             ss[j] = s; }
;         const float sa = wave_sum(ss[0] + ss[1]), s2 = wave_sum(ss[2]), s3 = wave_sum(ss[3]);
;         const float ra = 1.0f / sqrtf(sa * (1.0f / 1024.f) + EPS), rs = 1.0f / sqrtf(s2 * (1.0f / 512.f) + EPS), rg = 1.0f / sqrtf(s3 * (1.0f / 512.f) + EPS);
; #pragma unroll
;         for (int j = 0; j < 4; ++j) { const float r = (j < 2) ? ra : (j == 2 ? rs : rg);
;             u32x4 w; w.x = pk2(v[j][0] * r * gv[j][0], v[j][1] * r * gv[j][1]); w.y = pk2(v[j][2] * r * gv[j][2], v[j][3] * r * gv[j][3]);
;             w.z = pk2(v[j][4] * r * gv[j][4], v[j][5] * r * gv[j][5]); w.w = pk2(v[j][6] * r * gv[j][6], v[j][7] * r * gv[j][7]);
;             *(u32x4*)(yr + j * 512) = w; }
.LBB0_467:
	global_load_dwordx4 v[46:49], v[38:39], off
	global_load_dwordx4 v[54:57], v[38:39], off offset:1024
	global_load_dwordx4 v[34:37], v[38:39], off offset:2048
	global_load_dwordx4 v[30:33], v[38:39], off offset:3072
	s_add_i32 s4, s4, s6
	s_cmp_lt_i32 s4, 0x8000
	s_waitcnt vmcnt(3)
	v_and_b32_e32 v44, 0xffff0000, v46
	s_waitcnt vmcnt(2)
	v_and_b32_e32 v52, 0xffff0000, v54
	v_lshlrev_b32_e32 v42, 16, v46
	v_lshlrev_b32_e32 v50, 16, v54
	v_mov_b32_e32 v68, v44
	v_mov_b32_e32 v69, v52
	v_lshlrev_b32_e32 v43, 16, v47
	v_lshlrev_b32_e32 v51, 16, v55
	v_mov_b32_e32 v60, v42
	v_mov_b32_e32 v61, v50
	v_pk_mul_f32 v[68:69], v[68:69], v[68:69]
	v_and_b32_e32 v45, 0xffff0000, v47
	v_and_b32_e32 v53, 0xffff0000, v55
	v_mov_b32_e32 v70, v43
	v_mov_b32_e32 v71, v51
	v_pk_fma_f32 v[60:61], v[60:61], v[60:61], v[68:69]
	v_lshlrev_b32_e32 v46, 16, v48
	v_lshlrev_b32_e32 v54, 16, v56
	v_mov_b32_e32 v72, v45
	v_mov_b32_e32 v73, v53
	v_pk_fma_f32 v[60:61], v[70:71], v[70:71], v[60:61]
	v_and_b32_e32 v48, 0xffff0000, v48
	v_and_b32_e32 v56, 0xffff0000, v56
	v_mov_b32_e32 v74, v46
	v_mov_b32_e32 v75, v54
	v_pk_fma_f32 v[60:61], v[72:73], v[72:73], v[60:61]
	v_lshlrev_b32_e32 v47, 16, v49
	v_lshlrev_b32_e32 v55, 16, v57
	v_mov_b32_e32 v76, v48
	v_mov_b32_e32 v77, v56
	v_pk_fma_f32 v[60:61], v[74:75], v[74:75], v[60:61]
	v_and_b32_e32 v49, 0xffff0000, v49
	v_and_b32_e32 v57, 0xffff0000, v57
	v_mov_b32_e32 v78, v47
	v_mov_b32_e32 v79, v55
	v_pk_fma_f32 v[60:61], v[76:77], v[76:77], v[60:61]
	v_mov_b32_e32 v80, v49
	v_mov_b32_e32 v81, v57
	v_pk_fma_f32 v[60:61], v[78:79], v[78:79], v[60:61]
	s_waitcnt vmcnt(1)
	v_lshlrev_b32_e32 v59, 16, v35
	v_pk_fma_f32 v[60:61], v[80:81], v[80:81], v[60:61]
	v_lshlrev_b32_e32 v58, 16, v34
	v_add_f32_e32 v68, v60, v61
	ds_bpermute_b32 v69, v62, v68
	v_and_b32_e32 v61, 0xffff0000, v35
	v_and_b32_e32 v60, 0xffff0000, v34
	v_lshlrev_b32_e32 v35, 16, v37
	v_lshlrev_b32_e32 v34, 16, v36
	s_waitcnt lgkmcnt(0)
	v_add_f32_e32 v70, v68, v69
	ds_bpermute_b32 v71, v63, v70
	v_pk_mul_f32 v[68:69], v[58:59], v[58:59]
	v_and_b32_e32 v37, 0xffff0000, v37
	v_and_b32_e32 v36, 0xffff0000, v36
	v_mov_b32_e32 v72, v37
	s_waitcnt lgkmcnt(0)
	v_add_f32_e32 v74, v70, v71
	ds_bpermute_b32 v75, v64, v74
	v_pk_mul_f32 v[70:71], v[60:61], v[60:61]
	v_mov_b32_e32 v73, v35
	v_add_f32_e32 v68, v68, v70
	v_add_f32_e32 v68, v69, v68
	s_waitcnt lgkmcnt(0)
	v_add_f32_e32 v74, v74, v75
	ds_bpermute_b32 v75, v65, v74
	v_add_f32_e32 v68, v71, v68
	v_fmac_f32_e32 v68, v34, v34
	v_pk_mul_f32 v[72:73], v[72:73], v[72:73]
	v_fmac_f32_e32 v68, v36, v36
	s_waitcnt lgkmcnt(0)
	v_add_f32_e32 v69, v74, v75
	ds_bpermute_b32 v70, v66, v69
	v_add_f32_e32 v68, v73, v68
	v_add_f32_e32 v68, v72, v68
	ds_bpermute_b32 v71, v62, v68
	s_waitcnt lgkmcnt(1)
	v_add_f32_e32 v69, v69, v70
	ds_bpermute_b32 v70, v67, v69
	s_waitcnt lgkmcnt(1)
	v_add_f32_e32 v68, v68, v71
	ds_bpermute_b32 v71, v63, v68
	s_waitcnt lgkmcnt(1)
	v_add_f32_e32 v69, v69, v70
	v_fmamk_f32 v69, v69, 0x3a800000, v194
	v_mul_f32_e32 v70, 0x4f800000, v69
	v_cmp_gt_f32_e32 vcc, s13, v69
	s_waitcnt lgkmcnt(0)
	v_add_f32_e32 v71, v68, v71
	v_cndmask_b32_e32 v69, v69, v70, vcc
	v_sqrt_f32_e32 v70, v69
	s_nop 0
	v_add_u32_e32 v68, -1, v70
	v_add_u32_e32 v72, 1, v70
	v_fma_f32 v73, -v68, v70, v69
	v_fma_f32 v74, -v72, v70, v69
	v_cmp_ge_f32_e64 s[0:1], 0, v73
	s_nop 1
	v_cndmask_b32_e64 v68, v70, v68, s[0:1]
	v_cmp_lt_f32_e64 s[0:1], 0, v74
	s_nop 1
	v_cndmask_b32_e64 v68, v68, v72, s[0:1]
	v_mul_f32_e32 v70, 0x37800000, v68
	v_cndmask_b32_e32 v68, v68, v70, vcc
	v_cmp_class_f32_e32 vcc, v69, v195
	ds_bpermute_b32 v72, v64, v71
	s_nop 0
	v_cndmask_b32_e32 v68, v68, v69, vcc
	v_div_scale_f32 v69, s[0:1], v68, v68, 1.0
	v_rcp_f32_e32 v70, v69
	v_div_scale_f32 v73, vcc, 1.0, v68, 1.0
	v_fma_f32 v74, -v69, v70, 1.0
	v_fmac_f32_e32 v70, v74, v70
	v_mul_f32_e32 v74, v73, v70
	v_fma_f32 v75, -v69, v74, v73
	v_fmac_f32_e32 v74, v75, v70
	v_fma_f32 v69, -v69, v74, v73
	v_div_fmas_f32 v69, v69, v70, v74
	v_div_fixup_f32 v68, v69, v68, 1.0
	v_pk_mul_f32 v[42:43], v[68:69], v[42:43] op_sel_hi:[0,1]
	v_pk_mul_f32 v[46:47], v[68:69], v[46:47] op_sel_hi:[0,1]
	v_pk_mul_f32 v[48:49], v[68:69], v[48:49] op_sel_hi:[0,1]
	v_pk_mul_f32 v[44:45], v[68:69], v[44:45] op_sel_hi:[0,1]
	v_pk_mul_f32 v[50:51], v[68:69], v[50:51] op_sel_hi:[0,1]
	v_pk_mul_f32 v[52:53], v[68:69], v[52:53] op_sel_hi:[0,1]
	v_pk_mul_f32 v[54:55], v[68:69], v[54:55] op_sel_hi:[0,1]
	v_pk_mul_f32 v[56:57], v[68:69], v[56:57] op_sel_hi:[0,1]
	v_pk_mul_f32 v[68:69], v[16:17], v[42:43]
	v_pk_mul_f32 v[46:47], v[20:21], v[46:47]
	v_pk_mul_f32 v[48:49], v[18:19], v[48:49]
	v_pk_mul_f32 v[44:45], v[14:15], v[44:45]
	v_pk_mul_f32 v[42:43], v[24:25], v[50:51]
	v_pk_mul_f32 v[50:51], v[22:23], v[52:53]
	v_pk_mul_f32 v[52:53], v[28:29], v[54:55]
	v_pk_mul_f32 v[54:55], v[26:27], v[56:57]
	v_cvt_pk_bf16_f32 v46, v46, v48
	v_cvt_pk_bf16_f32 v47, v47, v49
	v_cvt_pk_bf16_f32 v44, v68, v44
	v_cvt_pk_bf16_f32 v45, v69, v45
	global_store_dwordx4 v[38:39], v[44:47], off
	v_bfe_u32 v49, v52, 16, 1
	s_waitcnt lgkmcnt(0)
	v_add_f32_e32 v44, v71, v72
	ds_bpermute_b32 v45, v65, v44
	v_add3_u32 v49, v52, v49, s45
	v_cvt_pk_bf16_f32 v43, v43, v51
	v_bfe_u32 v78, v55, 16, 1
	s_waitcnt lgkmcnt(0)
	v_add_f32_e32 v44, v44, v45
	ds_bpermute_b32 v45, v66, v44
	v_cvt_pk_bf16_f32 v42, v42, v50
	v_lshrrev_b32_e32 v47, 16, v49
	v_add3_u32 v46, v55, v78, s45
	v_bfe_u32 v55, v53, 16, 1
	s_waitcnt lgkmcnt(0)
; __device__ __forceinline__ unsigned pk2(float lo, float hi) { return f2bf(lo) | (f2bf(hi) << 16); }
; __device__ __forceinline__ void phase_branch_norm(bf16_t* y, const float* ga, const float* gs, const float* gg, const Ctx cx) {
;     ...
;         for (int j = 0; j < 4; ++j) { const u32x4 w = *(const u32x4*)(yr + j * 512);
;             v[j][0] = bflo(w.x); v[j][1] = bfhi(w.x); v[j][2] = bflo(w.y); v[j][3] = bfhi(w.y); v[j][4] = bflo(w.z); v[j][5] = bfhi(w.z); v[j][6] = bflo(w.w); v[j][7] = bfhi(w.w);
;             float s = 0.f;
; #pragma unroll
;             for (int e = 0; e < 8; ++e) s += v[j][e] * v[j][e];
;             ss[j] = s; }
;         const float sa = wave_sum(ss[0] + ss[1]), s2 = wave_sum(ss[2]), s3 = wave_sum(ss[3]);
;         const float ra = 1.0f / sqrtf(sa * (1.0f / 1024.f) + EPS), rs = 1.0f / sqrtf(s2 * (1.0f / 512.f) + EPS), rg = 1.0f / sqrtf(s3 * (1.0f / 512.f) + EPS);
; #pragma unroll
;         for (int j = 0; j < 4; ++j) { const float r = (j < 2) ? ra : (j == 2 ? rs : rg);
;             u32x4 w; w.x = pk2(v[j][0] * r * gv[j][0], v[j][1] * r * gv[j][1]); w.y = pk2(v[j][2] * r * gv[j][2], v[j][3] * r * gv[j][3]);
;             w.z = pk2(v[j][4] * r * gv[j][4], v[j][5] * r * gv[j][5]); w.w = pk2(v[j][6] * r * gv[j][6], v[j][7] * r * gv[j][7]);
;             *(u32x4*)(yr + j * 512) = w; }
	v_add_f32_e32 v44, v44, v45
	ds_bpermute_b32 v45, v67, v44
	v_add3_u32 v53, v53, v55, s45
	v_bfe_u32 v79, v54, 16, 1
	v_add3_u32 v54, v54, v79, s45
	s_waitcnt lgkmcnt(0)
	v_add_f32_e32 v44, v44, v45
	v_fmamk_f32 v44, v44, 0x3b000000, v194
	v_mul_f32_e32 v45, 0x4f800000, v44
	v_cmp_gt_f32_e32 vcc, s13, v44
	v_cndmask_b32_e32 v48, v44, v45, vcc
	v_sqrt_f32_e32 v49, v48
	v_lshrrev_b32_e32 v44, 16, v53
	v_and_or_b32 v45, v46, s43, v44
	v_and_or_b32 v44, v54, s43, v47
	v_add_u32_e32 v46, -1, v49
	v_fma_f32 v47, -v46, v49, v48
	v_cmp_ge_f32_e64 s[0:1], 0, v47
	v_add_u32_e32 v47, 1, v49
	v_cndmask_b32_e64 v46, v49, v46, s[0:1]
	v_fma_f32 v49, -v47, v49, v48
	v_cmp_lt_f32_e64 s[0:1], 0, v49
	v_cndmask_b32_e64 v46, v46, v47, s[0:1]
	v_mul_f32_e32 v47, 0x37800000, v46
	v_cndmask_b32_e32 v46, v46, v47, vcc
	v_cmp_class_f32_e32 vcc, v48, v195
	v_cndmask_b32_e32 v46, v46, v48, vcc
	v_div_scale_f32 v47, s[0:1], v46, v46, 1.0
	v_rcp_f32_e32 v48, v47
	global_store_dwordx4 v[38:39], v[42:45], off offset:1024
	s_waitcnt vmcnt(2)
	v_lshlrev_b32_e32 v49, 16, v31
	v_and_b32_e32 v51, 0xffff0000, v31
	v_fma_f32 v42, -v47, v48, 1.0
	v_fmac_f32_e32 v48, v42, v48
	v_div_scale_f32 v42, vcc, 1.0, v46, 1.0
	v_mul_f32_e32 v43, v42, v48
	v_fma_f32 v44, -v47, v43, v42
	v_fmac_f32_e32 v43, v44, v48
	v_fma_f32 v42, -v47, v43, v42
	v_div_fmas_f32 v42, v42, v48, v43
	v_lshlrev_b32_e32 v48, 16, v30
	v_and_b32_e32 v50, 0xffff0000, v30
	v_pk_mul_f32 v[30:31], v[48:49], v[48:49]
	v_pk_mul_f32 v[52:53], v[50:51], v[50:51]
	v_lshlrev_b32_e32 v55, 16, v33
	v_add_f32_e32 v30, v30, v52
	v_add_f32_e32 v30, v31, v30
	v_lshlrev_b32_e32 v54, 16, v32
	v_and_b32_e32 v57, 0xffff0000, v33
	v_add_f32_e32 v30, v53, v30
	v_and_b32_e32 v56, 0xffff0000, v32
	v_mov_b32_e32 v32, v57
	v_mov_b32_e32 v33, v55
	v_fmac_f32_e32 v30, v54, v54
	v_pk_mul_f32 v[32:33], v[32:33], v[32:33]
	v_fmac_f32_e32 v30, v56, v56
	v_div_fixup_f32 v42, v42, v46, 1.0
	v_add_f32_e32 v30, v33, v30
	v_pk_mul_f32 v[44:45], v[42:43], v[58:59] op_sel_hi:[0,1]
	v_pk_mul_f32 v[46:47], v[42:43], v[60:61] op_sel_hi:[0,1]
	v_add_f32_e32 v43, v32, v30
	ds_bpermute_b32 v52, v62, v43
	v_pk_mul_f32 v[32:33], v[42:43], v[34:35] op_sel_hi:[0,1]
	v_pk_mul_f32 v[34:35], v[42:43], v[36:37] op_sel_hi:[0,1]
	v_pk_mul_f32 v[30:31], v[6:7], v[46:47]
	v_pk_mul_f32 v[32:33], v[12:13], v[32:33]
	s_waitcnt lgkmcnt(0)
	v_add_f32_e32 v36, v43, v52
	ds_bpermute_b32 v37, v63, v36
	v_bfe_u32 v46, v31, 16, 1
	v_pk_mul_f32 v[34:35], v[10:11], v[34:35]
	v_bfe_u32 v47, v30, 16, 1
	v_add3_u32 v31, v31, v46, s45
	s_waitcnt lgkmcnt(0)
	v_add_f32_e32 v36, v36, v37
	ds_bpermute_b32 v37, v64, v36
	v_add3_u32 v30, v30, v47, s45
	s_waitcnt lgkmcnt(0)
	v_add_f32_e32 v36, v36, v37
	ds_bpermute_b32 v37, v65, v36
	v_cvt_pk_bf16_f32 v32, v32, v34
	v_cvt_pk_bf16_f32 v33, v33, v35
	s_waitcnt lgkmcnt(0)
	v_add_f32_e32 v36, v36, v37
	ds_bpermute_b32 v37, v66, v36
	s_waitcnt lgkmcnt(0)
	v_add_f32_e32 v36, v36, v37
	ds_bpermute_b32 v37, v67, v36
	v_pk_mul_f32 v[44:45], v[8:9], v[44:45]
	s_waitcnt lgkmcnt(0)
	v_add_f32_e32 v36, v36, v37
	v_fmamk_f32 v36, v36, 0x3b000000, v194
	v_mul_f32_e32 v37, 0x4f800000, v36
	v_cmp_gt_f32_e32 vcc, s13, v36
	v_bfe_u32 v42, v44, 16, 1
	v_bfe_u32 v43, v45, 16, 1
	v_cndmask_b32_e32 v36, v36, v37, vcc
	v_sqrt_f32_e32 v37, v36
	v_add3_u32 v43, v45, v43, s45
	v_add3_u32 v42, v44, v42, s45
	v_lshrrev_b32_e32 v42, 16, v42
	v_add_u32_e32 v34, -1, v37
	v_fma_f32 v35, -v34, v37, v36
	v_cmp_ge_f32_e64 s[0:1], 0, v35
	v_add_u32_e32 v35, 1, v37
	v_lshrrev_b32_e32 v43, 16, v43
	v_cndmask_b32_e64 v34, v37, v34, s[0:1]
	v_fma_f32 v37, -v35, v37, v36
	v_cmp_lt_f32_e64 s[0:1], 0, v37
	v_and_or_b32 v31, v31, s43, v43
	v_and_or_b32 v30, v30, s43, v42
	v_cndmask_b32_e64 v34, v34, v35, s[0:1]
	v_mul_f32_e32 v35, 0x37800000, v34
	v_cndmask_b32_e32 v34, v34, v35, vcc
	v_cmp_class_f32_e32 vcc, v36, v195
	global_store_dwordx4 v[38:39], v[30:33], off offset:2048
	s_nop 0
	v_cndmask_b32_e32 v34, v34, v36, vcc
	v_div_scale_f32 v35, s[0:1], v34, v34, 1.0
	v_rcp_f32_e32 v36, v35
	s_nop 0
	v_fma_f32 v30, -v35, v36, 1.0
	v_fmac_f32_e32 v36, v30, v36
	v_div_scale_f32 v30, vcc, 1.0, v34, 1.0
	v_mul_f32_e32 v31, v30, v36
	v_fma_f32 v32, -v35, v31, v30
	v_fmac_f32_e32 v31, v32, v36
	v_fma_f32 v30, -v35, v31, v30
	v_div_fmas_f32 v30, v30, v36, v31
	v_div_fixup_f32 v30, v30, v34, 1.0
	v_pk_mul_f32 v[32:33], v[30:31], v[48:49] op_sel_hi:[0,1]
	v_pk_mul_f32 v[34:35], v[30:31], v[50:51] op_sel_hi:[0,1]
	v_pk_mul_f32 v[36:37], v[30:31], v[54:55] op_sel_hi:[0,1]
	v_pk_mul_f32 v[30:31], v[30:31], v[56:57] op_sel_hi:[0,1]
	v_pk_mul_f32 v[34:35], v[40:41], v[34:35]
	v_pk_mul_f32 v[30:31], v[2:3], v[30:31]
	v_pk_mul_f32 v[32:33], v[0:1], v[32:33]
	v_pk_mul_f32 v[36:37], v[4:5], v[36:37]
	v_bfe_u32 v42, v31, 16, 1
	v_bfe_u32 v43, v30, 16, 1
	v_bfe_u32 v44, v35, 16, 1
	v_bfe_u32 v45, v34, 16, 1
	v_add3_u32 v34, v34, v45, s45
	v_add3_u32 v35, v35, v44, s45
	v_add3_u32 v30, v30, v43, s45
	v_add3_u32 v31, v31, v42, s45
	v_bfe_u32 v42, v32, 16, 1
	v_bfe_u32 v43, v33, 16, 1
	v_bfe_u32 v44, v36, 16, 1
	v_bfe_u32 v45, v37, 16, 1
	v_add3_u32 v37, v37, v45, s45
	v_add3_u32 v36, v36, v44, s45
	v_add3_u32 v33, v33, v43, s45
	v_add3_u32 v32, v32, v42, s45
	v_lshrrev_b32_e32 v42, 16, v32
	v_lshrrev_b32_e32 v43, 16, v33
	v_lshrrev_b32_e32 v32, 16, v36
	v_lshrrev_b32_e32 v33, 16, v37
	v_and_or_b32 v33, v31, s43, v33
	v_and_or_b32 v32, v30, s43, v32
	v_and_or_b32 v31, v35, s43, v43
	v_and_or_b32 v30, v34, s43, v42
	global_store_dwordx4 v[38:39], v[30:33], off offset:3072
	v_lshl_add_u64 v[38:39], v[38:39], 0, s[8:9]
	s_cbranch_scc1 .LBB0_467
